# hyena: epilogue gate/bias/weight loads issued before the Toeplitz MFMA loop into unused registers
# baseline (speedup 1.0000x reference)
.LBB0_483:
	v_mov_b32_e32 v6, 0
	v_mov_b32_e32 v12, 0
	v_mov_b32_e32 v13, 0
	v_mov_b32_e32 v14, 0
	v_mov_b32_e32 v15, 0
	ds_write_b128 v160, v[8:11]
	s_waitcnt lgkmcnt(0)
	s_barrier
	s_and_saveexec_b64 s[60:61], s[4:5]
	ds_read_b128 v[12:15], v160 offset:16
	s_or_b64 exec, exec, s[60:61]
	v_perm_b32 v17, v9, v10, s65
	v_perm_b32 v18, v10, v11, s65
	s_waitcnt lgkmcnt(0)
	v_perm_b32 v19, v11, v12, s65
	v_perm_b32 v16, v8, v9, s65
	v_pk_mov_b32 v[20:21], v[8:9], v[10:11] op_sel:[1,0]
	v_pk_mov_b32 v[22:23], v[10:11], v[12:13] op_sel:[1,0]
	v_perm_b32 v27, v12, v13, s65
	v_mov_b32_e32 v24, v17
	v_mov_b32_e32 v25, v18
	v_mov_b32_e32 v26, v19
	ds_write_b128 v160, v[16:19] offset:8224
	ds_write_b128 v160, v[20:23] offset:16448
	ds_write_b128 v160, v[24:27] offset:24672
	ds_write_b128 v160, v[10:13] offset:32896
	v_perm_b32 v11, v13, v14, s65
	v_mov_b32_e32 v8, v18
	v_mov_b32_e32 v9, v19
	v_mov_b32_e32 v10, v27
	v_pk_mov_b32 v[24:25], v[12:13], v[14:15] op_sel:[1,0]
	v_perm_b32 v15, v14, v15, s65
	v_mov_b32_e32 v12, v19
	v_mov_b32_e32 v13, v27
	v_mov_b32_e32 v14, v11
	ds_write_b128 v160, v[8:11] offset:41120
	ds_write_b128 v160, v[22:25] offset:49344
	ds_write_b128 v160, v[12:15] offset:57568
	s_waitcnt lgkmcnt(0)
	s_barrier
	s_add_u32 s2, s74, s58
	s_addc_u32 s3, s75, s59
	v_mov_b32_e32 v187, 0
	global_load_dword v227, v187, s[2:3]
	global_load_dword v246, v187, s[2:3] offset:2048
	global_load_dword v247, v187, s[44:45] offset:2048
	global_load_dword v244, v187, s[48:49] offset:2048
	global_load_dword v245, v158, s[44:45]
	global_load_dword v242, v157, s[44:45] offset:2048
	s_lshl_b64 s[2:3], s[50:51], 16
	v_lshl_add_u64 v[188:189], v[144:145], 0, s[2:3]
	global_load_dwordx2 v[190:191], v[188:189], off
	global_load_dwordx2 v[194:195], v[188:189], off offset:32
	global_load_dwordx2 v[196:197], v[188:189], off offset:64
	global_load_dwordx2 v[198:199], v[188:189], off offset:96
	global_load_dwordx2 v[200:201], v[188:189], off offset:128
	global_load_dwordx2 v[202:203], v[188:189], off offset:160
	global_load_dwordx2 v[204:205], v[188:189], off offset:192
	global_load_dwordx2 v[206:207], v[188:189], off offset:224
	global_load_dwordx2 v[208:209], v[188:189], off offset:256
	global_load_dwordx2 v[210:211], v[188:189], off offset:288
	global_load_dwordx2 v[212:213], v[188:189], off offset:320
	global_load_dwordx2 v[214:215], v[188:189], off offset:352
	v_lshl_add_u64 v[216:217], v[146:147], 1, v[188:189]
	global_load_ushort v243, v[216:217], off
	global_load_dwordx2 v[218:219], v[188:189], off offset:384
	global_load_dwordx2 v[220:221], v[188:189], off offset:416
	global_load_dwordx2 v[222:223], v[188:189], off offset:448
	global_load_dwordx2 v[224:225], v[188:189], off offset:480
	v_lshl_add_u64 v[188:189], v[188:189], 0, v[140:141]
	global_load_ushort v240, v[188:189], off offset:480
	ds_read_b128 v[70:73], v161 offset:4096
	ds_read_b128 v[66:69], v161 offset:4064
	ds_read_b128 v[78:81], v161 offset:4032
	ds_read_b128 v[74:77], v161 offset:4000
	ds_read_b128 v[86:89], v161 offset:3968
	ds_read_b128 v[82:85], v161 offset:3936
	ds_read_b128 v[94:97], v161 offset:3904
	ds_read_b128 v[90:93], v161 offset:3872
	ds_read_b128 v[102:105], v161 offset:3840
	ds_read_b128 v[98:101], v161 offset:3808
	ds_read_b128 v[110:113], v161 offset:3776
	ds_read_b128 v[106:109], v161 offset:3744
	ds_read_b128 v[118:121], v161 offset:3712
	ds_read_b128 v[114:117], v161 offset:3680
	ds_read_b128 v[122:125], v161 offset:3616
	ds_read_b128 v[126:129], v161 offset:3648
	v_add_u32_e32 v1, v153, v152
	ds_read_b128 v[134:137], v1
	s_mov_b32 s2, 0
	v_mov_b32_e32 v7, v6
	v_mov_b32_e32 v8, v6
	v_mov_b32_e32 v9, v6
	v_mov_b32_e32 v10, v6
	v_mov_b32_e32 v11, v6
	v_mov_b32_e32 v12, v6
	v_mov_b32_e32 v13, v6
	v_mov_b32_e32 v14, v6
	v_mov_b32_e32 v15, v6
	v_mov_b32_e32 v16, v6
	v_mov_b32_e32 v17, v6
	v_mov_b32_e32 v18, v6
	v_mov_b32_e32 v19, v6
	v_mov_b32_e32 v20, v6
	v_mov_b32_e32 v21, v6
	v_mov_b32_e32 v22, v6
	v_mov_b32_e32 v23, v6
	v_mov_b32_e32 v24, v6
	v_mov_b32_e32 v25, v6
	v_mov_b32_e32 v26, v6
	v_mov_b32_e32 v27, v6
	v_mov_b32_e32 v28, v6
	v_mov_b32_e32 v29, v6
	v_mov_b32_e32 v30, v6
	v_mov_b32_e32 v31, v6
	v_mov_b32_e32 v32, v6
	v_mov_b32_e32 v33, v6
	v_mov_b32_e32 v34, v6
	v_mov_b32_e32 v35, v6
	v_mov_b32_e32 v36, v6
	v_mov_b32_e32 v37, v6
	v_mov_b32_e32 v38, v6
	v_mov_b32_e32 v39, v6
	v_mov_b32_e32 v40, v6
	v_mov_b32_e32 v41, v6
	v_mov_b32_e32 v42, v6
	v_mov_b32_e32 v43, v6
	v_mov_b32_e32 v44, v6
	v_mov_b32_e32 v45, v6
	v_mov_b32_e32 v46, v6
	v_mov_b32_e32 v47, v6
	v_mov_b32_e32 v48, v6
	v_mov_b32_e32 v49, v6
	v_mov_b32_e32 v50, v6
	v_mov_b32_e32 v51, v6
	v_mov_b32_e32 v52, v6
	v_mov_b32_e32 v53, v6
	v_mov_b32_e32 v54, v6
	v_mov_b32_e32 v55, v6
	v_mov_b32_e32 v56, v6
	v_mov_b32_e32 v57, v6
	v_mov_b32_e32 v58, v6
	v_mov_b32_e32 v59, v6
	v_mov_b32_e32 v60, v6
	v_mov_b32_e32 v61, v6
	v_mov_b32_e32 v62, v6
	v_mov_b32_e32 v63, v6
	v_mov_b32_e32 v64, v6
	v_mov_b32_e32 v65, v6
	v_mov_b32_e32 v130, v6
	v_mov_b32_e32 v131, v6
	v_mov_b32_e32 v132, v6
	v_mov_b32_e32 v133, v6
.LBB0_486:
	v_add_u32_e32 v0, s2, v154
	v_add_u32_e32 v165, s2, v155
	s_waitcnt lgkmcnt(0)
	v_mfma_f32_16x16x32_bf16 v[10:13], v[126:129], v[134:137], v[10:13]
	v_add_u32_e32 v166, 0x10140, v165
	v_mfma_f32_16x16x32_bf16 v[6:9], v[122:125], v[134:137], v[6:9]
	ds_read_b128 v[122:125], v0
	ds_read_b128 v[126:129], v0 offset:32
	ds_read_b128 v[166:169], v166
	v_mfma_f32_16x16x32_bf16 v[130:133], v[70:73], v[134:137], v[130:133]
	v_mfma_f32_16x16x32_bf16 v[62:65], v[66:69], v[134:137], v[62:65]
	v_mfma_f32_16x16x32_bf16 v[58:61], v[78:81], v[134:137], v[58:61]
	v_mfma_f32_16x16x32_bf16 v[54:57], v[74:77], v[134:137], v[54:57]
	v_mfma_f32_16x16x32_bf16 v[50:53], v[86:89], v[134:137], v[50:53]
	v_mfma_f32_16x16x32_bf16 v[46:49], v[82:85], v[134:137], v[46:49]
	v_mfma_f32_16x16x32_bf16 v[42:45], v[94:97], v[134:137], v[42:45]
	v_mfma_f32_16x16x32_bf16 v[38:41], v[90:93], v[134:137], v[38:41]
	v_mfma_f32_16x16x32_bf16 v[34:37], v[102:105], v[134:137], v[34:37]
	v_mfma_f32_16x16x32_bf16 v[30:33], v[98:101], v[134:137], v[30:33]
	v_mfma_f32_16x16x32_bf16 v[26:29], v[110:113], v[134:137], v[26:29]
	v_mfma_f32_16x16x32_bf16 v[22:25], v[106:109], v[134:137], v[22:25]
	v_mfma_f32_16x16x32_bf16 v[18:21], v[118:121], v[134:137], v[18:21]
	v_mfma_f32_16x16x32_bf16 v[14:17], v[114:117], v[134:137], v[14:17]
	v_add_u32_e32 v134, 0x10180, v165
	s_waitcnt lgkmcnt(0)
	v_mfma_f32_16x16x32_bf16 v[10:13], v[118:121], v[166:169], v[10:13]
	v_mfma_f32_16x16x32_bf16 v[6:9], v[114:117], v[166:169], v[6:9]
	ds_read_b128 v[114:117], v0 offset:64
	ds_read_b128 v[118:121], v0 offset:96
	ds_read_b128 v[134:137], v134
	v_mfma_f32_16x16x32_bf16 v[130:133], v[126:129], v[166:169], v[130:133]
	v_mfma_f32_16x16x32_bf16 v[62:65], v[122:125], v[166:169], v[62:65]
	v_mfma_f32_16x16x32_bf16 v[58:61], v[70:73], v[166:169], v[58:61]
	v_mfma_f32_16x16x32_bf16 v[54:57], v[66:69], v[166:169], v[54:57]
	v_mfma_f32_16x16x32_bf16 v[50:53], v[78:81], v[166:169], v[50:53]
	v_mfma_f32_16x16x32_bf16 v[46:49], v[74:77], v[166:169], v[46:49]
	v_mfma_f32_16x16x32_bf16 v[42:45], v[86:89], v[166:169], v[42:45]
	v_mfma_f32_16x16x32_bf16 v[38:41], v[82:85], v[166:169], v[38:41]
	v_mfma_f32_16x16x32_bf16 v[34:37], v[94:97], v[166:169], v[34:37]
	v_mfma_f32_16x16x32_bf16 v[30:33], v[90:93], v[166:169], v[30:33]
	v_mfma_f32_16x16x32_bf16 v[26:29], v[102:105], v[166:169], v[26:29]
	v_mfma_f32_16x16x32_bf16 v[22:25], v[98:101], v[166:169], v[22:25]
	v_mfma_f32_16x16x32_bf16 v[18:21], v[110:113], v[166:169], v[18:21]
	v_mfma_f32_16x16x32_bf16 v[14:17], v[106:109], v[166:169], v[14:17]
	s_waitcnt lgkmcnt(0)
	v_mfma_f32_16x16x32_bf16 v[10:13], v[110:113], v[134:137], v[10:13]
	v_add_u32_e32 v166, 0x101c0, v165
	v_mfma_f32_16x16x32_bf16 v[6:9], v[106:109], v[134:137], v[6:9]
	ds_read_b128 v[106:109], v0 offset:128
	ds_read_b128 v[110:113], v0 offset:160
	ds_read_b128 v[166:169], v166
	v_mfma_f32_16x16x32_bf16 v[130:133], v[118:121], v[134:137], v[130:133]
	v_mfma_f32_16x16x32_bf16 v[62:65], v[114:117], v[134:137], v[62:65]
	v_mfma_f32_16x16x32_bf16 v[58:61], v[126:129], v[134:137], v[58:61]
	v_mfma_f32_16x16x32_bf16 v[54:57], v[122:125], v[134:137], v[54:57]
	v_mfma_f32_16x16x32_bf16 v[50:53], v[70:73], v[134:137], v[50:53]
	v_mfma_f32_16x16x32_bf16 v[46:49], v[66:69], v[134:137], v[46:49]
	v_mfma_f32_16x16x32_bf16 v[42:45], v[78:81], v[134:137], v[42:45]
	v_mfma_f32_16x16x32_bf16 v[38:41], v[74:77], v[134:137], v[38:41]
	v_mfma_f32_16x16x32_bf16 v[34:37], v[86:89], v[134:137], v[34:37]
	v_mfma_f32_16x16x32_bf16 v[30:33], v[82:85], v[134:137], v[30:33]
	v_mfma_f32_16x16x32_bf16 v[26:29], v[94:97], v[134:137], v[26:29]
	v_mfma_f32_16x16x32_bf16 v[22:25], v[90:93], v[134:137], v[22:25]
	v_mfma_f32_16x16x32_bf16 v[18:21], v[102:105], v[134:137], v[18:21]
	v_mfma_f32_16x16x32_bf16 v[14:17], v[98:101], v[134:137], v[14:17]
	v_add_u32_e32 v134, 0x10200, v165
	s_waitcnt lgkmcnt(0)
	v_mfma_f32_16x16x32_bf16 v[10:13], v[102:105], v[166:169], v[10:13]
	v_mfma_f32_16x16x32_bf16 v[6:9], v[98:101], v[166:169], v[6:9]
	ds_read_b128 v[98:101], v0 offset:192
	ds_read_b128 v[102:105], v0 offset:224
	ds_read_b128 v[134:137], v134
	v_mfma_f32_16x16x32_bf16 v[130:133], v[110:113], v[166:169], v[130:133]
	v_mfma_f32_16x16x32_bf16 v[62:65], v[106:109], v[166:169], v[62:65]
	v_mfma_f32_16x16x32_bf16 v[58:61], v[118:121], v[166:169], v[58:61]
	v_mfma_f32_16x16x32_bf16 v[54:57], v[114:117], v[166:169], v[54:57]
	v_mfma_f32_16x16x32_bf16 v[50:53], v[126:129], v[166:169], v[50:53]
	v_mfma_f32_16x16x32_bf16 v[46:49], v[122:125], v[166:169], v[46:49]
	v_mfma_f32_16x16x32_bf16 v[42:45], v[70:73], v[166:169], v[42:45]
	v_mfma_f32_16x16x32_bf16 v[38:41], v[66:69], v[166:169], v[38:41]
	v_mfma_f32_16x16x32_bf16 v[34:37], v[78:81], v[166:169], v[34:37]
	v_mfma_f32_16x16x32_bf16 v[30:33], v[74:77], v[166:169], v[30:33]
	v_mfma_f32_16x16x32_bf16 v[26:29], v[86:89], v[166:169], v[26:29]
	v_mfma_f32_16x16x32_bf16 v[22:25], v[82:85], v[166:169], v[22:25]
	v_mfma_f32_16x16x32_bf16 v[18:21], v[94:97], v[166:169], v[18:21]
	v_mfma_f32_16x16x32_bf16 v[14:17], v[90:93], v[166:169], v[14:17]
	s_waitcnt lgkmcnt(0)
	v_mfma_f32_16x16x32_bf16 v[10:13], v[94:97], v[134:137], v[10:13]
	v_add_u32_e32 v166, 0x10240, v165
	v_mfma_f32_16x16x32_bf16 v[6:9], v[90:93], v[134:137], v[6:9]
	ds_read_b128 v[90:93], v0 offset:256
	ds_read_b128 v[94:97], v0 offset:288
	ds_read_b128 v[166:169], v166
	v_mfma_f32_16x16x32_bf16 v[130:133], v[102:105], v[134:137], v[130:133]
	v_mfma_f32_16x16x32_bf16 v[62:65], v[98:101], v[134:137], v[62:65]
	v_mfma_f32_16x16x32_bf16 v[58:61], v[110:113], v[134:137], v[58:61]
	v_mfma_f32_16x16x32_bf16 v[54:57], v[106:109], v[134:137], v[54:57]
	v_mfma_f32_16x16x32_bf16 v[50:53], v[118:121], v[134:137], v[50:53]
	v_mfma_f32_16x16x32_bf16 v[46:49], v[114:117], v[134:137], v[46:49]
	v_mfma_f32_16x16x32_bf16 v[42:45], v[126:129], v[134:137], v[42:45]
	v_mfma_f32_16x16x32_bf16 v[38:41], v[122:125], v[134:137], v[38:41]
	v_mfma_f32_16x16x32_bf16 v[34:37], v[70:73], v[134:137], v[34:37]
	v_mfma_f32_16x16x32_bf16 v[30:33], v[66:69], v[134:137], v[30:33]
	v_mfma_f32_16x16x32_bf16 v[26:29], v[78:81], v[134:137], v[26:29]
	v_mfma_f32_16x16x32_bf16 v[22:25], v[74:77], v[134:137], v[22:25]
	v_mfma_f32_16x16x32_bf16 v[18:21], v[86:89], v[134:137], v[18:21]
	v_mfma_f32_16x16x32_bf16 v[14:17], v[82:85], v[134:137], v[14:17]
	v_add_u32_e32 v134, 0x10280, v165
	s_waitcnt lgkmcnt(0)
	v_mfma_f32_16x16x32_bf16 v[10:13], v[86:89], v[166:169], v[10:13]
	v_mfma_f32_16x16x32_bf16 v[6:9], v[82:85], v[166:169], v[6:9]
	ds_read_b128 v[82:85], v0 offset:320
	ds_read_b128 v[86:89], v0 offset:352
	ds_read_b128 v[134:137], v134
	v_mfma_f32_16x16x32_bf16 v[130:133], v[94:97], v[166:169], v[130:133]
	v_mfma_f32_16x16x32_bf16 v[62:65], v[90:93], v[166:169], v[62:65]
	v_mfma_f32_16x16x32_bf16 v[58:61], v[102:105], v[166:169], v[58:61]
	v_mfma_f32_16x16x32_bf16 v[54:57], v[98:101], v[166:169], v[54:57]
	v_mfma_f32_16x16x32_bf16 v[50:53], v[110:113], v[166:169], v[50:53]
	v_mfma_f32_16x16x32_bf16 v[46:49], v[106:109], v[166:169], v[46:49]
	v_mfma_f32_16x16x32_bf16 v[42:45], v[118:121], v[166:169], v[42:45]
	v_mfma_f32_16x16x32_bf16 v[38:41], v[114:117], v[166:169], v[38:41]
	v_mfma_f32_16x16x32_bf16 v[34:37], v[126:129], v[166:169], v[34:37]
	v_mfma_f32_16x16x32_bf16 v[30:33], v[122:125], v[166:169], v[30:33]
	v_mfma_f32_16x16x32_bf16 v[26:29], v[70:73], v[166:169], v[26:29]
	v_mfma_f32_16x16x32_bf16 v[22:25], v[66:69], v[166:169], v[22:25]
	v_mfma_f32_16x16x32_bf16 v[18:21], v[78:81], v[166:169], v[18:21]
	v_mfma_f32_16x16x32_bf16 v[14:17], v[74:77], v[166:169], v[14:17]
	s_waitcnt lgkmcnt(0)
	v_mfma_f32_16x16x32_bf16 v[10:13], v[78:81], v[134:137], v[10:13]
	v_add_u32_e32 v166, 0x102c0, v165
	v_mfma_f32_16x16x32_bf16 v[6:9], v[74:77], v[134:137], v[6:9]
	ds_read_b128 v[74:77], v0 offset:384
	ds_read_b128 v[78:81], v0 offset:416
	ds_read_b128 v[166:169], v166
	v_mfma_f32_16x16x32_bf16 v[130:133], v[86:89], v[134:137], v[130:133]
	v_mfma_f32_16x16x32_bf16 v[62:65], v[82:85], v[134:137], v[62:65]
	v_mfma_f32_16x16x32_bf16 v[58:61], v[94:97], v[134:137], v[58:61]
	v_mfma_f32_16x16x32_bf16 v[54:57], v[90:93], v[134:137], v[54:57]
	v_mfma_f32_16x16x32_bf16 v[50:53], v[102:105], v[134:137], v[50:53]
	v_mfma_f32_16x16x32_bf16 v[46:49], v[98:101], v[134:137], v[46:49]
	v_mfma_f32_16x16x32_bf16 v[42:45], v[110:113], v[134:137], v[42:45]
	v_mfma_f32_16x16x32_bf16 v[38:41], v[106:109], v[134:137], v[38:41]
	v_mfma_f32_16x16x32_bf16 v[34:37], v[118:121], v[134:137], v[34:37]
	v_mfma_f32_16x16x32_bf16 v[30:33], v[114:117], v[134:137], v[30:33]
	v_mfma_f32_16x16x32_bf16 v[26:29], v[126:129], v[134:137], v[26:29]
	v_mfma_f32_16x16x32_bf16 v[22:25], v[122:125], v[134:137], v[22:25]
	v_mfma_f32_16x16x32_bf16 v[18:21], v[70:73], v[134:137], v[18:21]
	v_mfma_f32_16x16x32_bf16 v[14:17], v[66:69], v[134:137], v[14:17]
	s_waitcnt lgkmcnt(0)
	v_mfma_f32_16x16x32_bf16 v[10:13], v[70:73], v[166:169], v[10:13]
	v_mfma_f32_16x16x32_bf16 v[6:9], v[66:69], v[166:169], v[6:9]
	ds_read_b128 v[66:69], v0 offset:448
	ds_read_b128 v[70:73], v0 offset:480
	v_add_u32_e32 v0, 0x10300, v165
	ds_read_b128 v[134:137], v0
	v_mfma_f32_16x16x32_bf16 v[130:133], v[78:81], v[166:169], v[130:133]
	v_mfma_f32_16x16x32_bf16 v[62:65], v[74:77], v[166:169], v[62:65]
	v_mfma_f32_16x16x32_bf16 v[58:61], v[86:89], v[166:169], v[58:61]
	v_mfma_f32_16x16x32_bf16 v[54:57], v[82:85], v[166:169], v[54:57]
	v_mfma_f32_16x16x32_bf16 v[50:53], v[94:97], v[166:169], v[50:53]
	v_mfma_f32_16x16x32_bf16 v[46:49], v[90:93], v[166:169], v[46:49]
	v_mfma_f32_16x16x32_bf16 v[42:45], v[102:105], v[166:169], v[42:45]
	v_mfma_f32_16x16x32_bf16 v[38:41], v[98:101], v[166:169], v[38:41]
	v_mfma_f32_16x16x32_bf16 v[34:37], v[110:113], v[166:169], v[34:37]
	v_mfma_f32_16x16x32_bf16 v[30:33], v[106:109], v[166:169], v[30:33]
	v_mfma_f32_16x16x32_bf16 v[26:29], v[118:121], v[166:169], v[26:29]
	v_mfma_f32_16x16x32_bf16 v[22:25], v[114:117], v[166:169], v[22:25]
	v_mfma_f32_16x16x32_bf16 v[18:21], v[126:129], v[166:169], v[18:21]
	v_mfma_f32_16x16x32_bf16 v[14:17], v[122:125], v[166:169], v[14:17]
	s_addk_i32 s2, 0x200
	s_cmpk_lg_i32 s2, 0x1000
	s_cbranch_scc1 .LBB0_486
	s_waitcnt vmcnt(0) lgkmcnt(0)
	s_add_u32 s2, s74, s58
	s_addc_u32 s3, s75, s59
	v_mov_b32_e32 v0, 0
	s_waitcnt lgkmcnt(2)
	v_mov_b32_e32 v66, v227
	s_waitcnt lgkmcnt(0)
	v_mov_b32_e32 v134, v246
	v_mov_b32_e32 v72, v247
	v_mov_b32_e32 v74, v244
	v_mov_b32_e32 v70, v245
	v_mov_b32_e32 v68, v242
	s_lshl_b64 s[2:3], s[50:51], 16
	v_lshl_add_u64 v[82:83], v[144:145], 0, s[2:3]
	v_mov_b32_e32 v84, v190
	v_mov_b32_e32 v85, v191
	v_mov_b32_e32 v136, v194
	v_mov_b32_e32 v137, v195
	v_mov_b32_e32 v128, v196
	v_mov_b32_e32 v129, v197
	v_mov_b32_e32 v124, v198
	v_mov_b32_e32 v125, v199
	v_mov_b32_e32 v120, v200
	v_mov_b32_e32 v121, v201
	v_mov_b32_e32 v116, v202
	v_mov_b32_e32 v117, v203
	v_mov_b32_e32 v112, v204
	v_mov_b32_e32 v113, v205
	v_mov_b32_e32 v108, v206
	v_mov_b32_e32 v109, v207
	v_mov_b32_e32 v104, v208
	v_mov_b32_e32 v105, v209
	v_mov_b32_e32 v100, v210
	v_mov_b32_e32 v101, v211
	v_mov_b32_e32 v94, v212
	v_mov_b32_e32 v95, v213
	v_mov_b32_e32 v90, v214
	v_mov_b32_e32 v91, v215
	v_lshl_add_u64 v[76:77], v[146:147], 1, v[82:83]
	v_mov_b32_e32 v67, v243
	v_mov_b32_e32 v86, v218
	v_mov_b32_e32 v87, v219
	v_mov_b32_e32 v80, v220
	v_mov_b32_e32 v81, v221
	v_mov_b32_e32 v78, v222
	v_mov_b32_e32 v79, v223
	s_nop 0
	v_mov_b32_e32 v76, v224
	v_mov_b32_e32 v77, v225
	v_lshl_add_u64 v[82:83], v[82:83], 0, v[140:141]
	v_mov_b32_e32 v89, v240
	s_waitcnt vmcnt(0) lgkmcnt(0)
	ds_bpermute_b32 v69, v162, v85
	v_cndmask_b32_e64 v71, v84, v136, s[12:13]
	v_cndmask_b32_e64 v73, v137, v85, s[10:11]
	v_cndmask_b32_e64 v82, v129, v137, s[10:11]
	v_cndmask_b32_e64 v92, v124, v120, s[12:13]
	s_waitcnt lgkmcnt(0)
	v_lshrrev_b32_e32 v69, 16, v69
	v_cndmask_b32_e64 v99, v113, v117, s[10:11]
	v_cndmask_b32_e64 v102, v112, v108, s[12:13]
	v_cndmask_b32_e64 v93, v121, v125, s[10:11]
	v_cndmask_b32_e64 v111, v101, v105, s[10:11]
	v_cndmask_b32_e64 v115, v95, v101, s[10:11]
	v_cndmask_b32_e64 v119, v91, v95, s[10:11]
	v_cndmask_b32_e64 v67, v67, 0, s[8:9]
	v_cndmask_b32_e64 v96, v120, v116, s[12:13]
	v_cndmask_b32_e64 v103, v109, v113, s[10:11]
	ds_bpermute_b32 v165, v163, v92
	ds_bpermute_b32 v92, v162, v99
	ds_bpermute_b32 v99, v163, v102
	ds_bpermute_b32 v102, v162, v111
	ds_bpermute_b32 v111, v162, v115
	ds_bpermute_b32 v115, v162, v119
	v_cndmask_b32_e64 v119, v69, v67, s[12:13]
	v_cndmask_b32_e64 v67, v87, v91, s[10:11]
	ds_bpermute_b32 v123, v163, v71
	ds_bpermute_b32 v71, v162, v73
	ds_bpermute_b32 v73, v162, v82
	ds_bpermute_b32 v82, v162, v93
	ds_bpermute_b32 v93, v163, v96
	ds_bpermute_b32 v96, v162, v103
	ds_bpermute_b32 v67, v162, v67
	v_cndmask_b32_e64 v75, v136, v128, s[12:13]
	v_cndmask_b32_e64 v88, v125, v129, s[10:11]
	v_cndmask_b32_e64 v114, v100, v94, s[12:13]
	ds_bpermute_b32 v127, v163, v75
	ds_bpermute_b32 v75, v162, v88
	ds_bpermute_b32 v186, v163, v114
	s_waitcnt lgkmcnt(8)
	v_and_b32_e32 v170, 0xffff0000, v71
	s_waitcnt lgkmcnt(4)
	v_and_b32_e32 v114, 0xffff0000, v96
	v_cndmask_b32_e64 v71, v81, v87, s[10:11]
	s_waitcnt lgkmcnt(3)
	v_and_b32_e32 v96, 0xffff0000, v67
	v_cndmask_b32_e64 v67, v86, v80, s[12:13]
	v_cndmask_b32_e64 v97, v117, v121, s[10:11]
	v_and_b32_e32 v172, 0xffff0000, v73
	ds_bpermute_b32 v71, v162, v71
	ds_bpermute_b32 v73, v163, v67
	v_cndmask_b32_e64 v67, v79, v81, s[10:11]
	ds_bpermute_b32 v88, v162, v97
	ds_bpermute_b32 v67, v162, v67
	v_cndmask_b32_e64 v69, v90, v86, s[12:13]
	v_cndmask_b32_e64 v83, v128, v124, s[12:13]
	v_cndmask_b32_e64 v118, v94, v90, s[12:13]
	s_waitcnt lgkmcnt(5)
	v_and_b32_e32 v174, 0xffff0000, v75
	ds_bpermute_b32 v75, v163, v69
	v_cndmask_b32_e64 v69, v80, v78, s[12:13]
	ds_bpermute_b32 v135, v163, v83
	ds_bpermute_b32 v83, v163, v118
	v_and_b32_e32 v118, 0xffff0000, v92
	s_waitcnt lgkmcnt(6)
	v_and_b32_e32 v92, 0xffff0000, v71
	ds_bpermute_b32 v71, v163, v69
	v_and_b32_e32 v167, 0xffff0000, v85
	s_waitcnt lgkmcnt(5)
	v_and_b32_e32 v122, 0xffff0000, v88
	v_cndmask_b32_e64 v69, v77, v79, s[10:11]
	s_waitcnt lgkmcnt(4)
	v_and_b32_e32 v88, 0xffff0000, v67
	ds_bpermute_b32 v67, v163, v76
	v_lshlrev_b32_e32 v178, 16, v85
	v_and_b32_e32 v166, 16, v85
	v_mov_b32_e32 v179, v167
	v_and_b32_e32 v126, 0xffff0000, v82
	ds_bpermute_b32 v82, v162, v69
	v_cndmask_b32_e64 v69, v78, v76, s[12:13]
	v_pk_mov_b32 v[180:181], v[166:167], v[178:179] op_sel:[1,0]
	ds_bpermute_b32 v69, v163, v69
	v_and_b32_e32 v176, 0xffff0000, v84
	v_mov_b32_e32 v177, v181
	s_waitcnt lgkmcnt(6)
	v_pk_fma_f32 v[166:167], v[72:73], v[176:177], v[74:75] op_sel_hi:[0,1,0]
	v_cndmask_b32_e64 v89, v89, 0, s[14:15]
	s_waitcnt lgkmcnt(3)
	v_pk_fma_f32 v[182:183], v[70:71], v[178:179], v[166:167] op_sel_hi:[0,1,1]
	ds_read2_b64 v[166:169], v164 offset1:4
	s_waitcnt lgkmcnt(3)
	v_cndmask_b32_e64 v67, v67, v89, s[10:11]
	v_lshlrev_b32_e32 v89, 16, v123
	v_mov_b32_e32 v181, v89
	s_waitcnt lgkmcnt(1)
	v_pk_fma_f32 v[180:181], v[68:69], v[180:181], v[182:183] op_sel_hi:[0,1,1]
	v_lshlrev_b32_e32 v182, 16, v119
	v_lshlrev_b32_e32 v183, 16, v84
	v_pk_fma_f32 v[84:85], v[72:73], v[182:183], v[74:75] op_sel_hi:[0,1,0]
	v_pk_mov_b32 v[182:183], v[182:183], v[176:177] op_sel:[1,0]
	s_waitcnt lgkmcnt(0)
	v_lshlrev_b32_e32 v184, 16, v166
	v_and_b32_e32 v185, 0xffff0000, v166
	v_pk_fma_f32 v[84:85], v[70:71], v[182:183], v[84:85] op_sel_hi:[0,1,1]
	v_mov_b32_e32 v177, v178
	v_pk_fma_f32 v[130:131], v[66:67], v[184:185], v[130:131] op_sel_hi:[0,1,1]
	v_pk_fma_f32 v[84:85], v[68:69], v[176:177], v[84:85] op_sel_hi:[0,1,1]
	v_pk_mul_f32 v[84:85], v[84:85], v[130:131]
	v_lshlrev_b32_e32 v130, 16, v167
	v_and_b32_e32 v131, 0xffff0000, v167
	v_pk_fma_f32 v[130:131], v[66:67], v[130:131], v[132:133] op_sel_hi:[0,1,1]
	v_and_b32_e32 v167, 0xffff0000, v137
	v_pk_mul_f32 v[130:131], v[180:181], v[130:131]
	v_lshlrev_b32_e32 v132, 16, v137
	v_and_b32_e32 v166, 16, v137
	v_mov_b32_e32 v133, v167
	v_cvt_pk_bf16_f32 v84, v84, v85
	v_cvt_pk_bf16_f32 v85, v130, v131
	v_lshlrev_b32_e32 v171, 16, v136
	v_and_b32_e32 v130, 0xffff0000, v136
	v_pk_mov_b32 v[136:137], v[166:167], v[132:133] op_sel:[1,0]
	v_lshlrev_b32_e32 v89, 16, v127
	v_mov_b32_e32 v131, v137
	v_pk_fma_f32 v[166:167], v[72:73], v[130:131], v[74:75] op_sel_hi:[0,1,0]
	v_mov_b32_e32 v137, v89
	v_pk_fma_f32 v[166:167], v[70:71], v[132:133], v[166:167] op_sel_hi:[0,1,1]
	v_pk_fma_f32 v[136:137], v[68:69], v[136:137], v[166:167] op_sel_hi:[0,1,1]
	v_pk_fma_f32 v[166:167], v[72:73], v[170:171], v[74:75] op_sel_hi:[0,1,0]
	v_pk_mov_b32 v[170:171], v[170:171], v[130:131] op_sel:[1,0]
	v_lshlrev_b32_e32 v176, 16, v168
	v_and_b32_e32 v177, 0xffff0000, v168
	v_pk_fma_f32 v[166:167], v[70:71], v[170:171], v[166:167] op_sel_hi:[0,1,1]
	v_mov_b32_e32 v131, v132
	v_pk_fma_f32 v[62:63], v[66:67], v[176:177], v[62:63] op_sel_hi:[0,1,1]
	v_pk_fma_f32 v[130:131], v[68:69], v[130:131], v[166:167] op_sel_hi:[0,1,1]
	v_pk_mul_f32 v[62:63], v[130:131], v[62:63]
	v_lshlrev_b32_e32 v130, 16, v169
	v_and_b32_e32 v131, 0xffff0000, v169
	v_pk_fma_f32 v[64:65], v[66:67], v[130:131], v[64:65] op_sel_hi:[0,1,1]
	v_pk_mul_f32 v[64:65], v[136:137], v[64:65]
	ds_read2_b64 v[130:133], v164 offset0:8 offset1:12
	v_and_b32_e32 v137, 0xffff0000, v129
	v_cvt_pk_bf16_f32 v62, v62, v63
	v_cvt_pk_bf16_f32 v63, v64, v65
	v_lshlrev_b32_e32 v173, 16, v128
	v_and_b32_e32 v64, 0xffff0000, v128
	v_lshlrev_b32_e32 v128, 16, v129
	v_and_b32_e32 v136, 16, v129
	v_mov_b32_e32 v129, v137
	v_pk_mov_b32 v[136:137], v[136:137], v[128:129] op_sel:[1,0]
	v_lshlrev_b32_e32 v89, 16, v135
	v_mov_b32_e32 v65, v137
	v_pk_fma_f32 v[166:167], v[72:73], v[64:65], v[74:75] op_sel_hi:[0,1,0]
	v_mov_b32_e32 v137, v89
	v_pk_fma_f32 v[166:167], v[70:71], v[128:129], v[166:167] op_sel_hi:[0,1,1]
	s_waitcnt lgkmcnt(0)
	v_lshlrev_b32_e32 v168, 16, v130
	v_and_b32_e32 v169, 0xffff0000, v130
	v_pk_fma_f32 v[136:137], v[68:69], v[136:137], v[166:167] op_sel_hi:[0,1,1]
	v_pk_fma_f32 v[166:167], v[72:73], v[172:173], v[74:75] op_sel_hi:[0,1,0]
	v_pk_fma_f32 v[58:59], v[66:67], v[168:169], v[58:59] op_sel_hi:[0,1,1]
	v_pk_mov_b32 v[168:169], v[172:173], v[64:65] op_sel:[1,0]
	v_mov_b32_e32 v65, v128
	v_pk_fma_f32 v[166:167], v[70:71], v[168:169], v[166:167] op_sel_hi:[0,1,1]
	v_pk_fma_f32 v[64:65], v[68:69], v[64:65], v[166:167] op_sel_hi:[0,1,1]
	v_pk_mul_f32 v[58:59], v[64:65], v[58:59]
	v_lshlrev_b32_e32 v64, 16, v131
	v_and_b32_e32 v65, 0xffff0000, v131
	v_pk_fma_f32 v[60:61], v[66:67], v[64:65], v[60:61] op_sel_hi:[0,1,1]
	v_and_b32_e32 v129, 0xffff0000, v125
	v_pk_mul_f32 v[60:61], v[136:137], v[60:61]
	v_lshlrev_b32_e32 v64, 16, v125
	v_and_b32_e32 v128, 16, v125
	v_mov_b32_e32 v65, v129
	v_cvt_pk_bf16_f32 v58, v58, v59
	v_cvt_pk_bf16_f32 v59, v60, v61
	v_lshlrev_b32_e32 v175, 16, v124
	v_and_b32_e32 v60, 0xffff0000, v124
	v_pk_mov_b32 v[124:125], v[128:129], v[64:65] op_sel:[1,0]
	v_lshlrev_b32_e32 v89, 16, v165
	v_mov_b32_e32 v61, v125
	v_pk_fma_f32 v[128:129], v[72:73], v[60:61], v[74:75] op_sel_hi:[0,1,0]
	v_mov_b32_e32 v125, v89
	v_pk_fma_f32 v[128:129], v[70:71], v[64:65], v[128:129] op_sel_hi:[0,1,1]
	v_lshlrev_b32_e32 v130, 16, v132
	v_and_b32_e32 v131, 0xffff0000, v132
	v_pk_fma_f32 v[124:125], v[68:69], v[124:125], v[128:129] op_sel_hi:[0,1,1]
	v_pk_fma_f32 v[128:129], v[72:73], v[174:175], v[74:75] op_sel_hi:[0,1,0]
	v_pk_fma_f32 v[54:55], v[66:67], v[130:131], v[54:55] op_sel_hi:[0,1,1]
	v_pk_mov_b32 v[130:131], v[174:175], v[60:61] op_sel:[1,0]
	v_mov_b32_e32 v61, v64
	v_pk_fma_f32 v[128:129], v[70:71], v[130:131], v[128:129] op_sel_hi:[0,1,1]
	v_pk_fma_f32 v[60:61], v[68:69], v[60:61], v[128:129] op_sel_hi:[0,1,1]
	v_pk_mul_f32 v[54:55], v[60:61], v[54:55]
	v_lshlrev_b32_e32 v60, 16, v133
	v_and_b32_e32 v61, 0xffff0000, v133
	ds_read2_b64 v[128:131], v164 offset0:16 offset1:20
	v_and_b32_e32 v65, 0xffff0000, v121
	v_pk_fma_f32 v[56:57], v[66:67], v[60:61], v[56:57] op_sel_hi:[0,1,1]
	v_lshlrev_b32_e32 v60, 16, v121
	v_and_b32_e32 v64, 16, v121
	v_mov_b32_e32 v61, v65
	v_pk_mul_f32 v[56:57], v[124:125], v[56:57]
	v_pk_mov_b32 v[64:65], v[64:65], v[60:61] op_sel:[1,0]
	v_cvt_pk_bf16_f32 v54, v54, v55
	v_cvt_pk_bf16_f32 v55, v56, v57
	v_and_b32_e32 v56, 0xffff0000, v120
	v_mov_b32_e32 v57, v65
	v_lshlrev_b32_e32 v89, 16, v93
	v_lshlrev_b32_e32 v127, 16, v120
	v_pk_fma_f32 v[120:121], v[72:73], v[56:57], v[74:75] op_sel_hi:[0,1,0]
	v_mov_b32_e32 v65, v89
	v_pk_fma_f32 v[120:121], v[70:71], v[60:61], v[120:121] op_sel_hi:[0,1,1]
	s_waitcnt lgkmcnt(0)
	v_lshlrev_b32_e32 v124, 16, v128
	v_and_b32_e32 v125, 0xffff0000, v128
	v_cndmask_b32_e64 v98, v116, v112, s[12:13]
	v_pk_fma_f32 v[64:65], v[68:69], v[64:65], v[120:121] op_sel_hi:[0,1,1]
	v_pk_fma_f32 v[120:121], v[72:73], v[126:127], v[74:75] op_sel_hi:[0,1,0]
	v_pk_fma_f32 v[50:51], v[66:67], v[124:125], v[50:51] op_sel_hi:[0,1,1]
	v_pk_mov_b32 v[124:125], v[126:127], v[56:57] op_sel:[1,0]
	ds_bpermute_b32 v97, v163, v98
	v_pk_fma_f32 v[120:121], v[70:71], v[124:125], v[120:121] op_sel_hi:[0,1,1]
	v_mov_b32_e32 v57, v60
	v_pk_fma_f32 v[56:57], v[68:69], v[56:57], v[120:121] op_sel_hi:[0,1,1]
	v_pk_mul_f32 v[50:51], v[56:57], v[50:51]
	v_lshlrev_b32_e32 v56, 16, v129
	v_and_b32_e32 v57, 0xffff0000, v129
	v_and_b32_e32 v61, 0xffff0000, v117
	v_pk_fma_f32 v[52:53], v[66:67], v[56:57], v[52:53] op_sel_hi:[0,1,1]
	v_lshlrev_b32_e32 v56, 16, v117
	v_and_b32_e32 v60, 16, v117
	v_mov_b32_e32 v57, v61
	v_pk_mul_f32 v[52:53], v[64:65], v[52:53]
	v_pk_mov_b32 v[60:61], v[60:61], v[56:57] op_sel:[1,0]
	v_cvt_pk_bf16_f32 v50, v50, v51
	v_cvt_pk_bf16_f32 v51, v52, v53
	s_waitcnt lgkmcnt(0)
	v_lshlrev_b32_e32 v64, 16, v97
	v_and_b32_e32 v52, 0xffff0000, v116
	v_mov_b32_e32 v53, v61
	v_mov_b32_e32 v61, v64
	v_pk_fma_f32 v[64:65], v[72:73], v[52:53], v[74:75] op_sel_hi:[0,1,0]
	v_lshlrev_b32_e32 v123, 16, v116
	v_pk_fma_f32 v[64:65], v[70:71], v[56:57], v[64:65] op_sel_hi:[0,1,1]
	v_lshlrev_b32_e32 v116, 16, v130
	v_and_b32_e32 v117, 0xffff0000, v130
	v_pk_fma_f32 v[60:61], v[68:69], v[60:61], v[64:65] op_sel_hi:[0,1,1]
	v_pk_fma_f32 v[64:65], v[72:73], v[122:123], v[74:75] op_sel_hi:[0,1,0]
	v_pk_fma_f32 v[46:47], v[66:67], v[116:117], v[46:47] op_sel_hi:[0,1,1]
	v_pk_mov_b32 v[116:117], v[122:123], v[52:53] op_sel:[1,0]
	v_mov_b32_e32 v53, v56
	v_pk_fma_f32 v[64:65], v[70:71], v[116:117], v[64:65] op_sel_hi:[0,1,1]
	v_pk_fma_f32 v[52:53], v[68:69], v[52:53], v[64:65] op_sel_hi:[0,1,1]
	v_pk_mul_f32 v[46:47], v[52:53], v[46:47]
	v_lshlrev_b32_e32 v52, 16, v131
	v_and_b32_e32 v53, 0xffff0000, v131
	ds_read2_b64 v[120:123], v164 offset0:24 offset1:28
	v_and_b32_e32 v57, 0xffff0000, v113
	v_pk_fma_f32 v[48:49], v[66:67], v[52:53], v[48:49] op_sel_hi:[0,1,1]
	v_lshlrev_b32_e32 v52, 16, v113
	v_and_b32_e32 v56, 16, v113
	v_mov_b32_e32 v53, v57
	v_pk_mul_f32 v[48:49], v[60:61], v[48:49]
	v_pk_mov_b32 v[56:57], v[56:57], v[52:53] op_sel:[1,0]
	v_cvt_pk_bf16_f32 v46, v46, v47
	v_cvt_pk_bf16_f32 v47, v48, v49
	v_lshlrev_b32_e32 v60, 16, v99
	v_and_b32_e32 v48, 0xffff0000, v112
	v_mov_b32_e32 v49, v57
	v_mov_b32_e32 v57, v60
	v_pk_fma_f32 v[60:61], v[72:73], v[48:49], v[74:75] op_sel_hi:[0,1,0]
	v_lshlrev_b32_e32 v119, 16, v112
	v_pk_fma_f32 v[60:61], v[70:71], v[52:53], v[60:61] op_sel_hi:[0,1,1]
	s_waitcnt lgkmcnt(0)
	v_lshlrev_b32_e32 v64, 16, v120
	v_and_b32_e32 v65, 0xffff0000, v120
	v_cndmask_b32_e64 v106, v108, v104, s[12:13]
	v_pk_fma_f32 v[56:57], v[68:69], v[56:57], v[60:61] op_sel_hi:[0,1,1]
	v_pk_fma_f32 v[60:61], v[72:73], v[118:119], v[74:75] op_sel_hi:[0,1,0]
	v_pk_fma_f32 v[42:43], v[66:67], v[64:65], v[42:43] op_sel_hi:[0,1,1]
	v_pk_mov_b32 v[64:65], v[118:119], v[48:49] op_sel:[1,0]
	ds_bpermute_b32 v103, v163, v106
	v_pk_fma_f32 v[60:61], v[70:71], v[64:65], v[60:61] op_sel_hi:[0,1,1]
	v_mov_b32_e32 v49, v52
	v_cndmask_b32_e64 v107, v105, v109, s[10:11]
	v_pk_fma_f32 v[48:49], v[68:69], v[48:49], v[60:61] op_sel_hi:[0,1,1]
	ds_bpermute_b32 v98, v162, v107
	v_pk_mul_f32 v[42:43], v[48:49], v[42:43]
	v_lshlrev_b32_e32 v48, 16, v121
	v_and_b32_e32 v49, 0xffff0000, v121
	v_and_b32_e32 v53, 0xffff0000, v109
	v_pk_fma_f32 v[44:45], v[66:67], v[48:49], v[44:45] op_sel_hi:[0,1,1]
	v_lshlrev_b32_e32 v48, 16, v109
	v_and_b32_e32 v52, 16, v109
	v_mov_b32_e32 v49, v53
	v_pk_mul_f32 v[44:45], v[56:57], v[44:45]
	v_pk_mov_b32 v[52:53], v[52:53], v[48:49] op_sel:[1,0]
	v_cvt_pk_bf16_f32 v42, v42, v43
	v_cvt_pk_bf16_f32 v43, v44, v45
	s_waitcnt lgkmcnt(1)
	v_lshlrev_b32_e32 v56, 16, v103
	v_and_b32_e32 v44, 0xffff0000, v108
	v_mov_b32_e32 v45, v53
	v_cndmask_b32_e64 v110, v104, v100, s[12:13]
	v_mov_b32_e32 v53, v56
	v_pk_fma_f32 v[56:57], v[72:73], v[44:45], v[74:75] op_sel_hi:[0,1,0]
	ds_bpermute_b32 v107, v163, v110
	s_waitcnt lgkmcnt(1)
	v_and_b32_e32 v110, 0xffff0000, v98
	v_and_b32_e32 v98, 0xffff0000, v115
	v_lshlrev_b32_e32 v115, 16, v108
	v_pk_fma_f32 v[56:57], v[70:71], v[48:49], v[56:57] op_sel_hi:[0,1,1]
	v_lshlrev_b32_e32 v60, 16, v122
	v_and_b32_e32 v61, 0xffff0000, v122
	v_pk_fma_f32 v[52:53], v[68:69], v[52:53], v[56:57] op_sel_hi:[0,1,1]
	v_pk_fma_f32 v[56:57], v[72:73], v[114:115], v[74:75] op_sel_hi:[0,1,0]
	v_pk_fma_f32 v[38:39], v[66:67], v[60:61], v[38:39] op_sel_hi:[0,1,1]
	v_pk_mov_b32 v[60:61], v[114:115], v[44:45] op_sel:[1,0]
	v_mov_b32_e32 v45, v48
	v_pk_fma_f32 v[56:57], v[70:71], v[60:61], v[56:57] op_sel_hi:[0,1,1]
	v_pk_fma_f32 v[44:45], v[68:69], v[44:45], v[56:57] op_sel_hi:[0,1,1]
	v_pk_mul_f32 v[38:39], v[44:45], v[38:39]
	v_lshlrev_b32_e32 v44, 16, v123
	v_and_b32_e32 v45, 0xffff0000, v123
	ds_read2_b64 v[112:115], v164 offset0:32 offset1:36
	v_and_b32_e32 v49, 0xffff0000, v105
	v_pk_fma_f32 v[40:41], v[66:67], v[44:45], v[40:41] op_sel_hi:[0,1,1]
	v_lshlrev_b32_e32 v44, 16, v105
	v_and_b32_e32 v48, 16, v105
	v_mov_b32_e32 v45, v49
	v_pk_mul_f32 v[40:41], v[52:53], v[40:41]
	v_pk_mov_b32 v[48:49], v[48:49], v[44:45] op_sel:[1,0]
	v_cvt_pk_bf16_f32 v38, v38, v39
	v_cvt_pk_bf16_f32 v39, v40, v41
	s_waitcnt lgkmcnt(1)
	v_lshlrev_b32_e32 v52, 16, v107
	v_and_b32_e32 v40, 0xffff0000, v104
	v_mov_b32_e32 v41, v49
	v_mov_b32_e32 v49, v52
	v_pk_fma_f32 v[52:53], v[72:73], v[40:41], v[74:75] op_sel_hi:[0,1,0]
	v_and_b32_e32 v106, 0xffff0000, v102
	v_and_b32_e32 v102, 0xffff0000, v111
	v_lshlrev_b32_e32 v111, 16, v104
	v_pk_fma_f32 v[52:53], v[70:71], v[44:45], v[52:53] op_sel_hi:[0,1,1]
	s_waitcnt lgkmcnt(0)
	v_lshlrev_b32_e32 v56, 16, v112
	v_and_b32_e32 v57, 0xffff0000, v112
	v_pk_fma_f32 v[48:49], v[68:69], v[48:49], v[52:53] op_sel_hi:[0,1,1]
	v_pk_fma_f32 v[52:53], v[72:73], v[110:111], v[74:75] op_sel_hi:[0,1,0]
	v_pk_fma_f32 v[34:35], v[66:67], v[56:57], v[34:35] op_sel_hi:[0,1,1]
	v_pk_mov_b32 v[56:57], v[110:111], v[40:41] op_sel:[1,0]
	v_mov_b32_e32 v41, v44
	v_pk_fma_f32 v[52:53], v[70:71], v[56:57], v[52:53] op_sel_hi:[0,1,1]
	v_pk_fma_f32 v[40:41], v[68:69], v[40:41], v[52:53] op_sel_hi:[0,1,1]
	v_pk_mul_f32 v[34:35], v[40:41], v[34:35]
	v_lshlrev_b32_e32 v40, 16, v113
	v_and_b32_e32 v41, 0xffff0000, v113
	v_and_b32_e32 v45, 0xffff0000, v101
	v_pk_fma_f32 v[36:37], v[66:67], v[40:41], v[36:37] op_sel_hi:[0,1,1]
	v_lshlrev_b32_e32 v40, 16, v101
	v_and_b32_e32 v44, 16, v101
	v_mov_b32_e32 v41, v45
	v_pk_mul_f32 v[36:37], v[48:49], v[36:37]
	v_pk_mov_b32 v[44:45], v[44:45], v[40:41] op_sel:[1,0]
	v_cvt_pk_bf16_f32 v34, v34, v35
	v_cvt_pk_bf16_f32 v35, v36, v37
	v_lshlrev_b32_e32 v48, 16, v186
	v_and_b32_e32 v36, 0xffff0000, v100
	v_mov_b32_e32 v37, v45
	v_mov_b32_e32 v45, v48
	v_pk_fma_f32 v[48:49], v[72:73], v[36:37], v[74:75] op_sel_hi:[0,1,0]
	v_lshlrev_b32_e32 v107, 16, v100
	v_pk_fma_f32 v[48:49], v[70:71], v[40:41], v[48:49] op_sel_hi:[0,1,1]
	v_lshlrev_b32_e32 v52, 16, v114
	v_and_b32_e32 v53, 0xffff0000, v114
	v_pk_fma_f32 v[44:45], v[68:69], v[44:45], v[48:49] op_sel_hi:[0,1,1]
	v_pk_fma_f32 v[48:49], v[72:73], v[106:107], v[74:75] op_sel_hi:[0,1,0]
	v_pk_fma_f32 v[30:31], v[66:67], v[52:53], v[30:31] op_sel_hi:[0,1,1]
	v_pk_mov_b32 v[52:53], v[106:107], v[36:37] op_sel:[1,0]
	v_mov_b32_e32 v37, v40
	v_pk_fma_f32 v[48:49], v[70:71], v[52:53], v[48:49] op_sel_hi:[0,1,1]
	v_pk_fma_f32 v[36:37], v[68:69], v[36:37], v[48:49] op_sel_hi:[0,1,1]
	v_pk_mul_f32 v[30:31], v[36:37], v[30:31]
	v_lshlrev_b32_e32 v36, 16, v115
	v_and_b32_e32 v37, 0xffff0000, v115
	ds_read2_b64 v[104:107], v164 offset0:40 offset1:44
	v_and_b32_e32 v41, 0xffff0000, v95
	v_pk_fma_f32 v[32:33], v[66:67], v[36:37], v[32:33] op_sel_hi:[0,1,1]
	v_lshlrev_b32_e32 v36, 16, v95
	v_and_b32_e32 v40, 16, v95
	v_mov_b32_e32 v37, v41
	v_pk_mul_f32 v[32:33], v[44:45], v[32:33]
	v_pk_mov_b32 v[40:41], v[40:41], v[36:37] op_sel:[1,0]
	v_cvt_pk_bf16_f32 v30, v30, v31
	v_cvt_pk_bf16_f32 v31, v32, v33
	v_lshlrev_b32_e32 v44, 16, v83
	v_and_b32_e32 v32, 0xffff0000, v94
	v_mov_b32_e32 v33, v41
	v_mov_b32_e32 v41, v44
	v_pk_fma_f32 v[44:45], v[72:73], v[32:33], v[74:75] op_sel_hi:[0,1,0]
	v_lshlrev_b32_e32 v103, 16, v94
	v_pk_fma_f32 v[44:45], v[70:71], v[36:37], v[44:45] op_sel_hi:[0,1,1]
	s_waitcnt lgkmcnt(0)
	v_lshlrev_b32_e32 v48, 16, v104
	v_and_b32_e32 v49, 0xffff0000, v104
	v_pk_fma_f32 v[40:41], v[68:69], v[40:41], v[44:45] op_sel_hi:[0,1,1]
	v_pk_fma_f32 v[44:45], v[72:73], v[102:103], v[74:75] op_sel_hi:[0,1,0]
	v_pk_fma_f32 v[26:27], v[66:67], v[48:49], v[26:27] op_sel_hi:[0,1,1]
	v_pk_mov_b32 v[48:49], v[102:103], v[32:33] op_sel:[1,0]
	v_mov_b32_e32 v33, v36
	v_pk_fma_f32 v[44:45], v[70:71], v[48:49], v[44:45] op_sel_hi:[0,1,1]
	v_pk_fma_f32 v[32:33], v[68:69], v[32:33], v[44:45] op_sel_hi:[0,1,1]
	v_pk_mul_f32 v[26:27], v[32:33], v[26:27]
	v_lshlrev_b32_e32 v32, 16, v105
	v_and_b32_e32 v33, 0xffff0000, v105
	v_and_b32_e32 v37, 0xffff0000, v91
	v_pk_fma_f32 v[28:29], v[66:67], v[32:33], v[28:29] op_sel_hi:[0,1,1]
	v_lshlrev_b32_e32 v32, 16, v91
	v_and_b32_e32 v36, 16, v91
	v_mov_b32_e32 v33, v37
	v_pk_mul_f32 v[28:29], v[40:41], v[28:29]
	v_pk_mov_b32 v[36:37], v[36:37], v[32:33] op_sel:[1,0]
	v_cvt_pk_bf16_f32 v26, v26, v27
	v_cvt_pk_bf16_f32 v27, v28, v29
	v_lshlrev_b32_e32 v40, 16, v75
	v_and_b32_e32 v28, 0xffff0000, v90
	v_mov_b32_e32 v29, v37
	v_mov_b32_e32 v37, v40
	v_pk_fma_f32 v[40:41], v[72:73], v[28:29], v[74:75] op_sel_hi:[0,1,0]
	v_lshlrev_b32_e32 v99, 16, v90
	v_pk_fma_f32 v[40:41], v[70:71], v[32:33], v[40:41] op_sel_hi:[0,1,1]
	v_lshlrev_b32_e32 v44, 16, v106
	v_and_b32_e32 v45, 0xffff0000, v106
	v_pk_fma_f32 v[36:37], v[68:69], v[36:37], v[40:41] op_sel_hi:[0,1,1]
	v_pk_fma_f32 v[40:41], v[72:73], v[98:99], v[74:75] op_sel_hi:[0,1,0]
	v_pk_fma_f32 v[22:23], v[66:67], v[44:45], v[22:23] op_sel_hi:[0,1,1]
	v_pk_mov_b32 v[44:45], v[98:99], v[28:29] op_sel:[1,0]
	v_mov_b32_e32 v29, v32
	v_pk_fma_f32 v[40:41], v[70:71], v[44:45], v[40:41] op_sel_hi:[0,1,1]
	v_pk_fma_f32 v[28:29], v[68:69], v[28:29], v[40:41] op_sel_hi:[0,1,1]
	v_pk_mul_f32 v[22:23], v[28:29], v[22:23]
	v_and_b32_e32 v41, 0xffff0000, v87
	v_cvt_pk_bf16_f32 v28, v22, v23
	v_lshlrev_b32_e32 v22, 16, v107
	v_and_b32_e32 v23, 0xffff0000, v107
	v_pk_fma_f32 v[22:23], v[66:67], v[22:23], v[24:25] op_sel_hi:[0,1,1]
	v_pk_mul_f32 v[22:23], v[36:37], v[22:23]
	v_lshlrev_b32_e32 v36, 16, v87
	v_cvt_pk_bf16_f32 v29, v22, v23
	ds_read2_b64 v[22:25], v164 offset0:48 offset1:52
	v_and_b32_e32 v40, 16, v87
	v_mov_b32_e32 v37, v41
	v_pk_mov_b32 v[40:41], v[40:41], v[36:37] op_sel:[1,0]
	v_lshlrev_b32_e32 v44, 16, v73
	v_and_b32_e32 v32, 0xffff0000, v86
	v_mov_b32_e32 v33, v41
	v_mov_b32_e32 v41, v44
	v_pk_fma_f32 v[44:45], v[72:73], v[32:33], v[74:75] op_sel_hi:[0,1,0]
	v_lshlrev_b32_e32 v97, 16, v86
	v_pk_fma_f32 v[44:45], v[70:71], v[36:37], v[44:45] op_sel_hi:[0,1,1]
	s_waitcnt lgkmcnt(0)
	v_lshlrev_b32_e32 v48, 16, v22
	v_and_b32_e32 v49, 0xffff0000, v22
	v_pk_fma_f32 v[40:41], v[68:69], v[40:41], v[44:45] op_sel_hi:[0,1,1]
	v_pk_fma_f32 v[44:45], v[72:73], v[96:97], v[74:75] op_sel_hi:[0,1,0]
	v_pk_fma_f32 v[18:19], v[66:67], v[48:49], v[18:19] op_sel_hi:[0,1,1]
	v_pk_mov_b32 v[48:49], v[96:97], v[32:33] op_sel:[1,0]
	v_mov_b32_e32 v33, v36
	v_pk_fma_f32 v[44:45], v[70:71], v[48:49], v[44:45] op_sel_hi:[0,1,1]
	v_pk_fma_f32 v[32:33], v[68:69], v[32:33], v[44:45] op_sel_hi:[0,1,1]
	v_pk_mul_f32 v[18:19], v[32:33], v[18:19]
	v_lshlrev_b32_e32 v22, 16, v23
	v_and_b32_e32 v23, 0xffff0000, v23
	v_and_b32_e32 v33, 0xffff0000, v81
	v_pk_fma_f32 v[20:21], v[66:67], v[22:23], v[20:21] op_sel_hi:[0,1,1]
	v_lshlrev_b32_e32 v22, 16, v81
	v_and_b32_e32 v32, 16, v81
	v_mov_b32_e32 v23, v33
	v_pk_mul_f32 v[20:21], v[40:41], v[20:21]
	v_pk_mov_b32 v[32:33], v[32:33], v[22:23] op_sel:[1,0]
	v_cvt_pk_bf16_f32 v18, v18, v19
	v_cvt_pk_bf16_f32 v19, v20, v21
	v_lshlrev_b32_e32 v36, 16, v71
	v_and_b32_e32 v20, 0xffff0000, v80
	v_mov_b32_e32 v21, v33
	v_mov_b32_e32 v33, v36
	v_pk_fma_f32 v[36:37], v[72:73], v[20:21], v[74:75] op_sel_hi:[0,1,0]
	v_lshlrev_b32_e32 v93, 16, v80
	v_pk_fma_f32 v[36:37], v[70:71], v[22:23], v[36:37] op_sel_hi:[0,1,1]
	v_lshlrev_b32_e32 v40, 16, v24
	v_and_b32_e32 v41, 0xffff0000, v24
	v_pk_fma_f32 v[32:33], v[68:69], v[32:33], v[36:37] op_sel_hi:[0,1,1]
	v_pk_fma_f32 v[36:37], v[72:73], v[92:93], v[74:75] op_sel_hi:[0,1,0]
	v_pk_fma_f32 v[14:15], v[66:67], v[40:41], v[14:15] op_sel_hi:[0,1,1]
	v_pk_mov_b32 v[40:41], v[92:93], v[20:21] op_sel:[1,0]
	v_mov_b32_e32 v21, v22
	v_pk_fma_f32 v[36:37], v[70:71], v[40:41], v[36:37] op_sel_hi:[0,1,1]
	v_pk_fma_f32 v[20:21], v[68:69], v[20:21], v[36:37] op_sel_hi:[0,1,1]
	v_pk_mul_f32 v[14:15], v[20:21], v[14:15]
	v_lshlrev_b32_e32 v24, 16, v79
	v_cvt_pk_bf16_f32 v20, v14, v15
	v_lshlrev_b32_e32 v14, 16, v25
	v_and_b32_e32 v15, 0xffff0000, v25
	v_pk_fma_f32 v[14:15], v[66:67], v[14:15], v[16:17] op_sel_hi:[0,1,1]
	v_pk_mul_f32 v[14:15], v[32:33], v[14:15]
	v_and_b32_e32 v33, 0xffff0000, v79
	v_cvt_pk_bf16_f32 v21, v14, v15
	ds_read2_b64 v[14:17], v164 offset0:56 offset1:60
	v_and_b32_e32 v32, 16, v79
	v_mov_b32_e32 v25, v33
	v_pk_mov_b32 v[32:33], v[32:33], v[24:25] op_sel:[1,0]
	v_lshlrev_b32_e32 v36, 16, v69
	v_and_b32_e32 v22, 0xffff0000, v78
	v_mov_b32_e32 v23, v33
	v_mov_b32_e32 v33, v36
	v_pk_fma_f32 v[36:37], v[72:73], v[22:23], v[74:75] op_sel_hi:[0,1,0]
	v_lshlrev_b32_e32 v89, 16, v78
	v_pk_fma_f32 v[36:37], v[70:71], v[24:25], v[36:37] op_sel_hi:[0,1,1]
	s_waitcnt lgkmcnt(0)
	v_lshlrev_b32_e32 v40, 16, v14
	v_and_b32_e32 v41, 0xffff0000, v14
	v_pk_fma_f32 v[32:33], v[68:69], v[32:33], v[36:37] op_sel_hi:[0,1,1]
	v_pk_fma_f32 v[36:37], v[72:73], v[88:89], v[74:75] op_sel_hi:[0,1,0]
	v_pk_fma_f32 v[10:11], v[66:67], v[40:41], v[10:11] op_sel_hi:[0,1,1]
	v_pk_mov_b32 v[40:41], v[88:89], v[22:23] op_sel:[1,0]
	v_mov_b32_e32 v23, v24
	v_pk_fma_f32 v[36:37], v[70:71], v[40:41], v[36:37] op_sel_hi:[0,1,1]
	v_pk_fma_f32 v[22:23], v[68:69], v[22:23], v[36:37] op_sel_hi:[0,1,1]
	v_pk_mul_f32 v[10:11], v[22:23], v[10:11]
	v_lshlrev_b32_e32 v14, 16, v15
	v_and_b32_e32 v15, 0xffff0000, v15
	v_and_b32_e32 v23, 0xffff0000, v77
	v_pk_fma_f32 v[12:13], v[66:67], v[14:15], v[12:13] op_sel_hi:[0,1,1]
	v_lshlrev_b32_e32 v14, 16, v77
	v_and_b32_e32 v22, 16, v77
	v_mov_b32_e32 v15, v23
	v_pk_mul_f32 v[12:13], v[32:33], v[12:13]
	v_pk_mov_b32 v[22:23], v[22:23], v[14:15] op_sel:[1,0]
	v_cvt_pk_bf16_f32 v10, v10, v11
	v_cvt_pk_bf16_f32 v11, v12, v13
	v_lshlrev_b32_e32 v24, 16, v67
	v_and_b32_e32 v12, 0xffff0000, v76
	v_mov_b32_e32 v13, v23
	v_mov_b32_e32 v23, v24
	v_pk_fma_f32 v[24:25], v[72:73], v[12:13], v[74:75] op_sel_hi:[0,1,0]
	v_and_b32_e32 v82, 0xffff0000, v82
	v_lshlrev_b32_e32 v83, 16, v76
	v_pk_fma_f32 v[24:25], v[70:71], v[14:15], v[24:25] op_sel_hi:[0,1,1]
	v_lshlrev_b32_e32 v32, 16, v16
	v_and_b32_e32 v33, 0xffff0000, v16
	v_pk_fma_f32 v[22:23], v[68:69], v[22:23], v[24:25] op_sel_hi:[0,1,1]
	v_pk_fma_f32 v[24:25], v[72:73], v[82:83], v[74:75] op_sel_hi:[0,1,0]
	v_pk_fma_f32 v[6:7], v[66:67], v[32:33], v[6:7] op_sel_hi:[0,1,1]
	v_pk_mov_b32 v[32:33], v[82:83], v[12:13] op_sel:[1,0]
	v_mov_b32_e32 v13, v14
	v_pk_fma_f32 v[24:25], v[70:71], v[32:33], v[24:25] op_sel_hi:[0,1,1]
	v_pk_fma_f32 v[12:13], v[68:69], v[12:13], v[24:25] op_sel_hi:[0,1,1]
	v_pk_mul_f32 v[6:7], v[12:13], v[6:7]
	v_lshlrev_b32_e32 v12, 16, v17
	v_and_b32_e32 v13, 0xffff0000, v17
	v_pk_fma_f32 v[8:9], v[66:67], v[12:13], v[8:9] op_sel_hi:[0,1,1]
	v_pk_mul_f32 v[8:9], v[22:23], v[8:9]
	v_cvt_pk_bf16_f32 v6, v6, v7
	v_cvt_pk_bf16_f32 v7, v8, v9
	s_barrier
	ds_write2_b64 v164, v[84:85], v[62:63] offset1:4
	ds_write2_b64 v164, v[58:59], v[54:55] offset0:8 offset1:12
	ds_write2_b64 v164, v[50:51], v[46:47] offset0:16 offset1:20
	ds_write2_b64 v164, v[42:43], v[38:39] offset0:24 offset1:28
	ds_write2_b64 v164, v[34:35], v[30:31] offset0:32 offset1:36
	ds_write2_b64 v164, v[26:27], v[28:29] offset0:40 offset1:44
	ds_write2_b64 v164, v[18:19], v[20:21] offset0:48 offset1:52
	ds_write2_b64 v164, v[10:11], v[6:7] offset0:56 offset1:60
	ds_write_b128 v160, v[2:5]
	v_mov_b32_e32 v6, 0
	v_mov_b32_e32 v7, 0
	v_mov_b32_e32 v8, 0
	v_mov_b32_e32 v9, 0
	s_waitcnt lgkmcnt(0)
	s_barrier
	s_and_saveexec_b64 s[50:51], s[4:5]
	ds_read_b128 v[6:9], v160 offset:16
	s_or_b64 exec, exec, s[50:51]
	v_perm_b32 v11, v3, v4, s65
	v_perm_b32 v12, v4, v5, s65
	s_waitcnt lgkmcnt(0)
	v_perm_b32 v13, v5, v6, s65
	v_perm_b32 v10, v2, v3, s65
	v_pk_mov_b32 v[14:15], v[2:3], v[4:5] op_sel:[1,0]
	v_pk_mov_b32 v[16:17], v[4:5], v[6:7] op_sel:[1,0]
	v_perm_b32 v21, v6, v7, s65
	v_mov_b32_e32 v18, v11
	v_mov_b32_e32 v19, v12
	v_mov_b32_e32 v20, v13
	ds_write_b128 v160, v[10:13] offset:8224
	ds_write_b128 v160, v[14:17] offset:16448
	ds_write_b128 v160, v[18:21] offset:24672
	ds_write_b128 v160, v[4:7] offset:32896
	v_perm_b32 v5, v7, v8, s65
	v_mov_b32_e32 v2, v12
	v_mov_b32_e32 v3, v13
	v_mov_b32_e32 v4, v21
	v_pk_mov_b32 v[18:19], v[6:7], v[8:9] op_sel:[1,0]
	v_perm_b32 v9, v8, v9, s65
	v_mov_b32_e32 v6, v13
	v_mov_b32_e32 v7, v21
	v_mov_b32_e32 v8, v5
	ds_write_b128 v160, v[2:5] offset:41120
	ds_write_b128 v160, v[16:19] offset:49344
	ds_write_b128 v160, v[6:9] offset:57568
	s_waitcnt lgkmcnt(0)
	s_barrier
	v_lshl_add_u64 v[188:189], v[144:145], 0, s[42:43]
	v_lshl_add_u64 v[190:191], v[188:189], 0, s[38:39]
	global_load_dword v187, v158, s[44:45] offset:2048
	global_load_dword v227, v159, s[44:45]
	global_load_dword v246, v156, s[44:45]
	global_load_dword v247, v156, s[48:49]
	v_lshl_add_u64 v[188:189], v[148:149], 0, s[42:43]
	global_load_dwordx2 v[194:195], v[190:191], off
	global_load_dwordx2 v[196:197], v[190:191], off offset:32
	global_load_dwordx2 v[198:199], v[190:191], off offset:64
	global_load_dwordx2 v[200:201], v[190:191], off offset:96
	global_load_dwordx2 v[202:203], v[190:191], off offset:128
	global_load_dwordx2 v[204:205], v[190:191], off offset:160
	global_load_dwordx2 v[206:207], v[190:191], off offset:192
	global_load_dwordx2 v[208:209], v[190:191], off offset:224
	global_load_dwordx2 v[210:211], v[190:191], off offset:256
	global_load_dwordx2 v[212:213], v[190:191], off offset:288
	global_load_dwordx2 v[214:215], v[190:191], off offset:320
	global_load_dwordx2 v[216:217], v[190:191], off offset:352
	global_load_dwordx2 v[218:219], v[190:191], off offset:384
	v_lshl_add_u64 v[220:221], v[146:147], 1, v[190:191]
	global_load_ushort v244, v[220:221], off
	global_load_dwordx2 v[222:223], v[190:191], off offset:416
	global_load_dwordx2 v[224:225], v[190:191], off offset:448
	global_load_dwordx2 v[228:229], v[190:191], off offset:480
	v_lshl_add_u64 v[190:191], v[190:191], 0, v[140:141]
	global_load_ushort v245, v[190:191], off offset:480
	ds_read_b128 v[64:67], v161 offset:4096
	ds_read_b128 v[60:63], v161 offset:4064
	ds_read_b128 v[72:75], v161 offset:4032
	ds_read_b128 v[68:71], v161 offset:4000
	ds_read_b128 v[80:83], v161 offset:3968
	ds_read_b128 v[76:79], v161 offset:3936
	ds_read_b128 v[88:91], v161 offset:3904
	ds_read_b128 v[84:87], v161 offset:3872
	ds_read_b128 v[96:99], v161 offset:3840
	ds_read_b128 v[92:95], v161 offset:3808
	ds_read_b128 v[104:107], v161 offset:3776
	ds_read_b128 v[100:103], v161 offset:3744
	ds_read_b128 v[112:115], v161 offset:3712
	ds_read_b128 v[108:111], v161 offset:3680
	ds_read_b128 v[116:119], v161 offset:3616
	ds_read_b128 v[120:123], v161 offset:3648
	ds_read_b128 v[128:131], v1
	s_mov_b32 s2, 0
	v_mov_b32_e32 v1, v0
	v_mov_b32_e32 v2, v0
	v_mov_b32_e32 v3, v0
	v_mov_b32_e32 v4, v0
	v_mov_b32_e32 v5, v0
	v_mov_b32_e32 v6, v0
	v_mov_b32_e32 v7, v0
	v_mov_b32_e32 v8, v0
	v_mov_b32_e32 v9, v0
	v_mov_b32_e32 v10, v0
	v_mov_b32_e32 v11, v0
	v_mov_b32_e32 v12, v0
	v_mov_b32_e32 v13, v0
	v_mov_b32_e32 v14, v0
	v_mov_b32_e32 v15, v0
	v_mov_b32_e32 v16, v0
	v_mov_b32_e32 v17, v0
	v_mov_b32_e32 v18, v0
	v_mov_b32_e32 v19, v0
	v_mov_b32_e32 v20, v0
	v_mov_b32_e32 v21, v0
	v_mov_b32_e32 v22, v0
	v_mov_b32_e32 v23, v0
	v_mov_b32_e32 v24, v0
	v_mov_b32_e32 v25, v0
	v_mov_b32_e32 v26, v0
	v_mov_b32_e32 v27, v0
	v_mov_b32_e32 v28, v0
	v_mov_b32_e32 v29, v0
	v_mov_b32_e32 v30, v0
	v_mov_b32_e32 v31, v0
	v_mov_b32_e32 v32, v0
	v_mov_b32_e32 v33, v0
	v_mov_b32_e32 v34, v0
	v_mov_b32_e32 v35, v0
	v_mov_b32_e32 v36, v0
	v_mov_b32_e32 v37, v0
	v_mov_b32_e32 v38, v0
	v_mov_b32_e32 v39, v0
	v_mov_b32_e32 v40, v0
	v_mov_b32_e32 v41, v0
	v_mov_b32_e32 v42, v0
	v_mov_b32_e32 v43, v0
	v_mov_b32_e32 v44, v0
	v_mov_b32_e32 v45, v0
	v_mov_b32_e32 v46, v0
	v_mov_b32_e32 v47, v0
	v_mov_b32_e32 v48, v0
	v_mov_b32_e32 v49, v0
	v_mov_b32_e32 v50, v0
	v_mov_b32_e32 v51, v0
	v_mov_b32_e32 v52, v0
	v_mov_b32_e32 v53, v0
	v_mov_b32_e32 v54, v0
	v_mov_b32_e32 v55, v0
	v_mov_b32_e32 v56, v0
	v_mov_b32_e32 v57, v0
	v_mov_b32_e32 v58, v0
	v_mov_b32_e32 v59, v0
	v_mov_b32_e32 v124, v0
	v_mov_b32_e32 v125, v0
	v_mov_b32_e32 v126, v0
	v_mov_b32_e32 v127, v0
.LBB0_490:
	v_add_u32_e32 v132, s2, v154
	v_add_u32_e32 v133, s2, v155
	s_waitcnt lgkmcnt(0)
	v_mfma_f32_16x16x32_bf16 v[4:7], v[120:123], v[128:131], v[4:7]
	v_add_u32_e32 v135, 0x10140, v133
	v_mfma_f32_16x16x32_bf16 v[0:3], v[116:119], v[128:131], v[0:3]
	ds_read_b128 v[116:119], v132
	ds_read_b128 v[120:123], v132 offset:32
	ds_read_b128 v[166:169], v135
	v_mfma_f32_16x16x32_bf16 v[124:127], v[64:67], v[128:131], v[124:127]
	v_mfma_f32_16x16x32_bf16 v[56:59], v[60:63], v[128:131], v[56:59]
	v_mfma_f32_16x16x32_bf16 v[52:55], v[72:75], v[128:131], v[52:55]
	v_mfma_f32_16x16x32_bf16 v[48:51], v[68:71], v[128:131], v[48:51]
	v_mfma_f32_16x16x32_bf16 v[44:47], v[80:83], v[128:131], v[44:47]
	v_mfma_f32_16x16x32_bf16 v[40:43], v[76:79], v[128:131], v[40:43]
	v_mfma_f32_16x16x32_bf16 v[36:39], v[88:91], v[128:131], v[36:39]
	v_mfma_f32_16x16x32_bf16 v[32:35], v[84:87], v[128:131], v[32:35]
	v_mfma_f32_16x16x32_bf16 v[28:31], v[96:99], v[128:131], v[28:31]
	v_mfma_f32_16x16x32_bf16 v[24:27], v[92:95], v[128:131], v[24:27]
	v_mfma_f32_16x16x32_bf16 v[20:23], v[104:107], v[128:131], v[20:23]
	v_mfma_f32_16x16x32_bf16 v[16:19], v[100:103], v[128:131], v[16:19]
	v_mfma_f32_16x16x32_bf16 v[12:15], v[112:115], v[128:131], v[12:15]
	v_mfma_f32_16x16x32_bf16 v[8:11], v[108:111], v[128:131], v[8:11]
	v_add_u32_e32 v128, 0x10180, v133
	s_waitcnt lgkmcnt(0)
	v_mfma_f32_16x16x32_bf16 v[4:7], v[112:115], v[166:169], v[4:7]
	v_mfma_f32_16x16x32_bf16 v[0:3], v[108:111], v[166:169], v[0:3]
	ds_read_b128 v[108:111], v132 offset:64
	ds_read_b128 v[112:115], v132 offset:96
	ds_read_b128 v[128:131], v128
	v_mfma_f32_16x16x32_bf16 v[124:127], v[120:123], v[166:169], v[124:127]
	v_mfma_f32_16x16x32_bf16 v[56:59], v[116:119], v[166:169], v[56:59]
	v_mfma_f32_16x16x32_bf16 v[52:55], v[64:67], v[166:169], v[52:55]
	v_mfma_f32_16x16x32_bf16 v[48:51], v[60:63], v[166:169], v[48:51]
	v_mfma_f32_16x16x32_bf16 v[44:47], v[72:75], v[166:169], v[44:47]
	v_mfma_f32_16x16x32_bf16 v[40:43], v[68:71], v[166:169], v[40:43]
	v_mfma_f32_16x16x32_bf16 v[36:39], v[80:83], v[166:169], v[36:39]
	v_mfma_f32_16x16x32_bf16 v[32:35], v[76:79], v[166:169], v[32:35]
	v_mfma_f32_16x16x32_bf16 v[28:31], v[88:91], v[166:169], v[28:31]
	v_mfma_f32_16x16x32_bf16 v[24:27], v[84:87], v[166:169], v[24:27]
	v_mfma_f32_16x16x32_bf16 v[20:23], v[96:99], v[166:169], v[20:23]
	v_mfma_f32_16x16x32_bf16 v[16:19], v[92:95], v[166:169], v[16:19]
	v_mfma_f32_16x16x32_bf16 v[12:15], v[104:107], v[166:169], v[12:15]
	v_mfma_f32_16x16x32_bf16 v[8:11], v[100:103], v[166:169], v[8:11]
	s_waitcnt lgkmcnt(0)
	v_mfma_f32_16x16x32_bf16 v[4:7], v[104:107], v[128:131], v[4:7]
	v_add_u32_e32 v135, 0x101c0, v133
	v_mfma_f32_16x16x32_bf16 v[0:3], v[100:103], v[128:131], v[0:3]
	ds_read_b128 v[100:103], v132 offset:128
	ds_read_b128 v[104:107], v132 offset:160
	ds_read_b128 v[166:169], v135
	v_mfma_f32_16x16x32_bf16 v[124:127], v[112:115], v[128:131], v[124:127]
	v_mfma_f32_16x16x32_bf16 v[56:59], v[108:111], v[128:131], v[56:59]
	v_mfma_f32_16x16x32_bf16 v[52:55], v[120:123], v[128:131], v[52:55]
	v_mfma_f32_16x16x32_bf16 v[48:51], v[116:119], v[128:131], v[48:51]
	v_mfma_f32_16x16x32_bf16 v[44:47], v[64:67], v[128:131], v[44:47]
	v_mfma_f32_16x16x32_bf16 v[40:43], v[60:63], v[128:131], v[40:43]
	v_mfma_f32_16x16x32_bf16 v[36:39], v[72:75], v[128:131], v[36:39]
	v_mfma_f32_16x16x32_bf16 v[32:35], v[68:71], v[128:131], v[32:35]
	v_mfma_f32_16x16x32_bf16 v[28:31], v[80:83], v[128:131], v[28:31]
	v_mfma_f32_16x16x32_bf16 v[24:27], v[76:79], v[128:131], v[24:27]
	v_mfma_f32_16x16x32_bf16 v[20:23], v[88:91], v[128:131], v[20:23]
	v_mfma_f32_16x16x32_bf16 v[16:19], v[84:87], v[128:131], v[16:19]
	v_mfma_f32_16x16x32_bf16 v[12:15], v[96:99], v[128:131], v[12:15]
	v_mfma_f32_16x16x32_bf16 v[8:11], v[92:95], v[128:131], v[8:11]
	v_add_u32_e32 v128, 0x10200, v133
	s_waitcnt lgkmcnt(0)
	v_mfma_f32_16x16x32_bf16 v[4:7], v[96:99], v[166:169], v[4:7]
	v_mfma_f32_16x16x32_bf16 v[0:3], v[92:95], v[166:169], v[0:3]
	ds_read_b128 v[92:95], v132 offset:192
	ds_read_b128 v[96:99], v132 offset:224
	ds_read_b128 v[128:131], v128
	v_mfma_f32_16x16x32_bf16 v[124:127], v[104:107], v[166:169], v[124:127]
	v_mfma_f32_16x16x32_bf16 v[56:59], v[100:103], v[166:169], v[56:59]
	v_mfma_f32_16x16x32_bf16 v[52:55], v[112:115], v[166:169], v[52:55]
	v_mfma_f32_16x16x32_bf16 v[48:51], v[108:111], v[166:169], v[48:51]
	v_mfma_f32_16x16x32_bf16 v[44:47], v[120:123], v[166:169], v[44:47]
	v_mfma_f32_16x16x32_bf16 v[40:43], v[116:119], v[166:169], v[40:43]
	v_mfma_f32_16x16x32_bf16 v[36:39], v[64:67], v[166:169], v[36:39]
	v_mfma_f32_16x16x32_bf16 v[32:35], v[60:63], v[166:169], v[32:35]
	v_mfma_f32_16x16x32_bf16 v[28:31], v[72:75], v[166:169], v[28:31]
	v_mfma_f32_16x16x32_bf16 v[24:27], v[68:71], v[166:169], v[24:27]
	v_mfma_f32_16x16x32_bf16 v[20:23], v[80:83], v[166:169], v[20:23]
	v_mfma_f32_16x16x32_bf16 v[16:19], v[76:79], v[166:169], v[16:19]
	v_mfma_f32_16x16x32_bf16 v[12:15], v[88:91], v[166:169], v[12:15]
	v_mfma_f32_16x16x32_bf16 v[8:11], v[84:87], v[166:169], v[8:11]
	s_waitcnt lgkmcnt(0)
	v_mfma_f32_16x16x32_bf16 v[4:7], v[88:91], v[128:131], v[4:7]
	v_add_u32_e32 v135, 0x10240, v133
	v_mfma_f32_16x16x32_bf16 v[0:3], v[84:87], v[128:131], v[0:3]
	ds_read_b128 v[84:87], v132 offset:256
	ds_read_b128 v[88:91], v132 offset:288
	ds_read_b128 v[166:169], v135
	v_mfma_f32_16x16x32_bf16 v[124:127], v[96:99], v[128:131], v[124:127]
	v_mfma_f32_16x16x32_bf16 v[56:59], v[92:95], v[128:131], v[56:59]
	v_mfma_f32_16x16x32_bf16 v[52:55], v[104:107], v[128:131], v[52:55]
	v_mfma_f32_16x16x32_bf16 v[48:51], v[100:103], v[128:131], v[48:51]
	v_mfma_f32_16x16x32_bf16 v[44:47], v[112:115], v[128:131], v[44:47]
	v_mfma_f32_16x16x32_bf16 v[40:43], v[108:111], v[128:131], v[40:43]
	v_mfma_f32_16x16x32_bf16 v[36:39], v[120:123], v[128:131], v[36:39]
	v_mfma_f32_16x16x32_bf16 v[32:35], v[116:119], v[128:131], v[32:35]
	v_mfma_f32_16x16x32_bf16 v[28:31], v[64:67], v[128:131], v[28:31]
	v_mfma_f32_16x16x32_bf16 v[24:27], v[60:63], v[128:131], v[24:27]
	v_mfma_f32_16x16x32_bf16 v[20:23], v[72:75], v[128:131], v[20:23]
	v_mfma_f32_16x16x32_bf16 v[16:19], v[68:71], v[128:131], v[16:19]
	v_mfma_f32_16x16x32_bf16 v[12:15], v[80:83], v[128:131], v[12:15]
	v_mfma_f32_16x16x32_bf16 v[8:11], v[76:79], v[128:131], v[8:11]
	v_add_u32_e32 v128, 0x10280, v133
	s_waitcnt lgkmcnt(0)
	v_mfma_f32_16x16x32_bf16 v[4:7], v[80:83], v[166:169], v[4:7]
	v_mfma_f32_16x16x32_bf16 v[0:3], v[76:79], v[166:169], v[0:3]
	ds_read_b128 v[76:79], v132 offset:320
	ds_read_b128 v[80:83], v132 offset:352
	ds_read_b128 v[128:131], v128
	v_mfma_f32_16x16x32_bf16 v[124:127], v[88:91], v[166:169], v[124:127]
	v_mfma_f32_16x16x32_bf16 v[56:59], v[84:87], v[166:169], v[56:59]
	v_mfma_f32_16x16x32_bf16 v[52:55], v[96:99], v[166:169], v[52:55]
	v_mfma_f32_16x16x32_bf16 v[48:51], v[92:95], v[166:169], v[48:51]
	v_mfma_f32_16x16x32_bf16 v[44:47], v[104:107], v[166:169], v[44:47]
	v_mfma_f32_16x16x32_bf16 v[40:43], v[100:103], v[166:169], v[40:43]
	v_mfma_f32_16x16x32_bf16 v[36:39], v[112:115], v[166:169], v[36:39]
	v_mfma_f32_16x16x32_bf16 v[32:35], v[108:111], v[166:169], v[32:35]
	v_mfma_f32_16x16x32_bf16 v[28:31], v[120:123], v[166:169], v[28:31]
	v_mfma_f32_16x16x32_bf16 v[24:27], v[116:119], v[166:169], v[24:27]
	v_mfma_f32_16x16x32_bf16 v[20:23], v[64:67], v[166:169], v[20:23]
	v_mfma_f32_16x16x32_bf16 v[16:19], v[60:63], v[166:169], v[16:19]
	v_mfma_f32_16x16x32_bf16 v[12:15], v[72:75], v[166:169], v[12:15]
	v_mfma_f32_16x16x32_bf16 v[8:11], v[68:71], v[166:169], v[8:11]
	s_waitcnt lgkmcnt(0)
	v_mfma_f32_16x16x32_bf16 v[4:7], v[72:75], v[128:131], v[4:7]
	v_add_u32_e32 v135, 0x102c0, v133
	v_mfma_f32_16x16x32_bf16 v[0:3], v[68:71], v[128:131], v[0:3]
	ds_read_b128 v[68:71], v132 offset:384
	ds_read_b128 v[72:75], v132 offset:416
	ds_read_b128 v[166:169], v135
	v_mfma_f32_16x16x32_bf16 v[124:127], v[80:83], v[128:131], v[124:127]
	v_mfma_f32_16x16x32_bf16 v[56:59], v[76:79], v[128:131], v[56:59]
	v_mfma_f32_16x16x32_bf16 v[52:55], v[88:91], v[128:131], v[52:55]
	v_mfma_f32_16x16x32_bf16 v[48:51], v[84:87], v[128:131], v[48:51]
	v_mfma_f32_16x16x32_bf16 v[44:47], v[96:99], v[128:131], v[44:47]
	v_mfma_f32_16x16x32_bf16 v[40:43], v[92:95], v[128:131], v[40:43]
	v_mfma_f32_16x16x32_bf16 v[36:39], v[104:107], v[128:131], v[36:39]
	v_mfma_f32_16x16x32_bf16 v[32:35], v[100:103], v[128:131], v[32:35]
	v_mfma_f32_16x16x32_bf16 v[28:31], v[112:115], v[128:131], v[28:31]
	v_mfma_f32_16x16x32_bf16 v[24:27], v[108:111], v[128:131], v[24:27]
	v_mfma_f32_16x16x32_bf16 v[20:23], v[120:123], v[128:131], v[20:23]
	v_mfma_f32_16x16x32_bf16 v[16:19], v[116:119], v[128:131], v[16:19]
	v_mfma_f32_16x16x32_bf16 v[12:15], v[64:67], v[128:131], v[12:15]
	v_mfma_f32_16x16x32_bf16 v[8:11], v[60:63], v[128:131], v[8:11]
	v_add_u32_e32 v128, 0x10300, v133
	s_waitcnt lgkmcnt(0)
	v_mfma_f32_16x16x32_bf16 v[4:7], v[64:67], v[166:169], v[4:7]
	v_mfma_f32_16x16x32_bf16 v[0:3], v[60:63], v[166:169], v[0:3]
	ds_read_b128 v[60:63], v132 offset:448
	ds_read_b128 v[64:67], v132 offset:480
	ds_read_b128 v[128:131], v128
	v_mfma_f32_16x16x32_bf16 v[124:127], v[72:75], v[166:169], v[124:127]
	v_mfma_f32_16x16x32_bf16 v[56:59], v[68:71], v[166:169], v[56:59]
	v_mfma_f32_16x16x32_bf16 v[52:55], v[80:83], v[166:169], v[52:55]
	v_mfma_f32_16x16x32_bf16 v[48:51], v[76:79], v[166:169], v[48:51]
	v_mfma_f32_16x16x32_bf16 v[44:47], v[88:91], v[166:169], v[44:47]
	v_mfma_f32_16x16x32_bf16 v[40:43], v[84:87], v[166:169], v[40:43]
	v_mfma_f32_16x16x32_bf16 v[36:39], v[96:99], v[166:169], v[36:39]
	v_mfma_f32_16x16x32_bf16 v[32:35], v[92:95], v[166:169], v[32:35]
	v_mfma_f32_16x16x32_bf16 v[28:31], v[104:107], v[166:169], v[28:31]
	v_mfma_f32_16x16x32_bf16 v[24:27], v[100:103], v[166:169], v[24:27]
	v_mfma_f32_16x16x32_bf16 v[20:23], v[112:115], v[166:169], v[20:23]
	v_mfma_f32_16x16x32_bf16 v[16:19], v[108:111], v[166:169], v[16:19]
	v_mfma_f32_16x16x32_bf16 v[12:15], v[120:123], v[166:169], v[12:15]
	v_mfma_f32_16x16x32_bf16 v[8:11], v[116:119], v[166:169], v[8:11]
	s_addk_i32 s2, 0x200
	s_cmpk_lg_i32 s2, 0x1000
	s_cbranch_scc1 .LBB0_490
	s_waitcnt vmcnt(0) lgkmcnt(0)
	s_waitcnt lgkmcnt(2)
	v_lshl_add_u64 v[60:61], v[144:145], 0, s[42:43]
	v_lshl_add_u64 v[76:77], v[60:61], 0, s[38:39]
	s_waitcnt lgkmcnt(1)
	v_mov_b32_e32 v64, v187
	v_mov_b32_e32 v62, v227
	v_mov_b32_e32 v66, v246
	v_mov_b32_e32 v68, v247
	v_lshl_add_u64 v[60:61], v[148:149], 0, s[42:43]
	v_mov_b32_e32 v122, v194
	v_mov_b32_e32 v123, v195
	s_waitcnt lgkmcnt(0)
	v_mov_b32_e32 v128, v196
	v_mov_b32_e32 v129, v197
	v_mov_b32_e32 v120, v198
	v_mov_b32_e32 v121, v199
	v_mov_b32_e32 v116, v200
	v_mov_b32_e32 v117, v201
	v_mov_b32_e32 v112, v202
	v_mov_b32_e32 v113, v203
	v_mov_b32_e32 v108, v204
	v_mov_b32_e32 v109, v205
	v_mov_b32_e32 v104, v206
	v_mov_b32_e32 v105, v207
	v_mov_b32_e32 v100, v208
	v_mov_b32_e32 v101, v209
	v_mov_b32_e32 v96, v210
	v_mov_b32_e32 v97, v211
	v_mov_b32_e32 v92, v212
	v_mov_b32_e32 v93, v213
	v_mov_b32_e32 v86, v214
	v_mov_b32_e32 v87, v215
	v_mov_b32_e32 v82, v216
	v_mov_b32_e32 v83, v217
	v_mov_b32_e32 v78, v218
	v_mov_b32_e32 v79, v219
	v_lshl_add_u64 v[70:71], v[146:147], 1, v[76:77]
	v_mov_b32_e32 v63, v244
	v_mov_b32_e32 v74, v222
	v_mov_b32_e32 v75, v223
	v_mov_b32_e32 v72, v224
	v_mov_b32_e32 v73, v225
	s_nop 0
	v_mov_b32_e32 v70, v228
	v_mov_b32_e32 v71, v229
	v_lshl_add_u64 v[76:77], v[76:77], 0, v[140:141]
	v_mov_b32_e32 v85, v245
	ds_read_b64 v[166:167], v164
	s_add_i32 s40, s40, s92
	s_cmpk_lt_i32 s40, 0x200
	s_waitcnt lgkmcnt(0)
	v_lshlrev_b32_e32 v176, 16, v166
	v_and_b32_e32 v177, 0xffff0000, v166
	s_waitcnt vmcnt(0)
	ds_bpermute_b32 v65, v162, v123
	v_cndmask_b32_e64 v67, v122, v128, s[12:13]
	v_cndmask_b32_e64 v69, v129, v123, s[10:11]
	v_cndmask_b32_e64 v77, v121, v129, s[10:11]
	v_cndmask_b32_e64 v88, v113, v117, s[10:11]
	ds_bpermute_b32 v119, v163, v67
	ds_bpermute_b32 v67, v162, v69
	ds_bpermute_b32 v69, v162, v77
	ds_bpermute_b32 v77, v162, v88
	s_waitcnt lgkmcnt(4)
	v_lshrrev_b32_e32 v65, 16, v65
	v_cndmask_b32_e64 v84, v116, v112, s[12:13]
	v_cndmask_b32_e64 v63, v63, 0, s[8:9]
	v_cndmask_b32_e64 v94, v105, v109, s[10:11]
	v_cndmask_b32_e64 v137, v65, v63, s[12:13]
	v_cndmask_b32_e64 v63, v82, v78, s[12:13]
	v_cndmask_b32_e64 v65, v75, v79, s[10:11]
	ds_bpermute_b32 v135, v163, v84
	ds_bpermute_b32 v84, v162, v94
	s_waitcnt lgkmcnt(2)
	v_and_b32_e32 v118, 0xffff0000, v77
	ds_bpermute_b32 v65, v162, v65
	ds_bpermute_b32 v77, v163, v63
	v_cndmask_b32_e64 v63, v78, v74, s[12:13]
	v_cndmask_b32_e64 v76, v128, v120, s[12:13]
	v_cndmask_b32_e64 v80, v120, v116, s[12:13]
	v_cndmask_b32_e64 v81, v117, v121, s[10:11]
	v_cndmask_b32_e64 v90, v109, v113, s[10:11]
	v_and_b32_e32 v132, 0xffff0000, v69
	ds_bpermute_b32 v69, v163, v63
	v_cndmask_b32_e64 v63, v73, v75, s[10:11]
	ds_bpermute_b32 v131, v163, v76
	ds_bpermute_b32 v133, v163, v80
	ds_bpermute_b32 v76, v162, v81
	ds_bpermute_b32 v80, v162, v90
	ds_bpermute_b32 v63, v162, v63
	v_cndmask_b32_e64 v107, v92, v86, s[12:13]
	v_cndmask_b32_e64 v110, v87, v93, s[10:11]
	ds_bpermute_b32 v165, v163, v107
	ds_bpermute_b32 v107, v162, v110
	s_waitcnt lgkmcnt(10)
	v_and_b32_e32 v110, 0xffff0000, v84
	s_waitcnt lgkmcnt(9)
	v_and_b32_e32 v84, 0xffff0000, v65
	v_cndmask_b32_e64 v65, v74, v72, s[12:13]
	v_cndmask_b32_e64 v111, v86, v82, s[12:13]
	v_cndmask_b32_e64 v114, v83, v87, s[10:11]
	v_and_b32_e32 v130, 0xffff0000, v67
	ds_bpermute_b32 v67, v163, v65
	v_cndmask_b32_e64 v65, v71, v73, s[10:11]
	ds_bpermute_b32 v81, v163, v111
	ds_bpermute_b32 v111, v162, v114
	s_waitcnt lgkmcnt(7)
	v_and_b32_e32 v136, 0xffff0000, v76
	s_waitcnt lgkmcnt(6)
	v_and_b32_e32 v114, 0xffff0000, v80
	ds_bpermute_b32 v76, v162, v65
	s_waitcnt lgkmcnt(6)
	v_and_b32_e32 v80, 0xffff0000, v63
	ds_bpermute_b32 v63, v163, v70
	v_cndmask_b32_e64 v65, v72, v70, s[12:13]
	ds_bpermute_b32 v65, v163, v65
	v_and_b32_e32 v173, 0xffff0000, v123
	v_lshlrev_b32_e32 v170, 16, v123
	v_and_b32_e32 v172, 16, v123
	v_mov_b32_e32 v171, v173
	v_pk_mov_b32 v[172:173], v[172:173], v[170:171] op_sel:[1,0]
	v_cndmask_b32_e64 v85, v85, 0, s[14:15]
	v_and_b32_e32 v168, 0xffff0000, v122
	v_mov_b32_e32 v169, v173
	s_waitcnt lgkmcnt(1)
	v_cndmask_b32_e64 v63, v63, v85, s[10:11]
	v_lshlrev_b32_e32 v85, 16, v119
	v_pk_fma_f32 v[174:175], v[66:67], v[168:169], v[68:69] op_sel_hi:[0,1,0]
	v_mov_b32_e32 v173, v85
	s_waitcnt lgkmcnt(0)
	v_pk_fma_f32 v[174:175], v[64:65], v[170:171], v[174:175] op_sel_hi:[0,1,1]
	v_pk_fma_f32 v[172:173], v[62:63], v[172:173], v[174:175] op_sel_hi:[0,1,1]
	v_lshlrev_b32_e32 v174, 16, v137
	v_lshlrev_b32_e32 v175, 16, v122
	v_pk_fma_f32 v[122:123], v[66:67], v[174:175], v[68:69] op_sel_hi:[0,1,0]
	v_pk_mov_b32 v[174:175], v[174:175], v[168:169] op_sel:[1,0]
	v_mov_b32_e32 v169, v170
	v_pk_fma_f32 v[122:123], v[64:65], v[174:175], v[122:123] op_sel_hi:[0,1,1]
	v_pk_fma_f32 v[124:125], v[134:135], v[176:177], v[124:125] op_sel_hi:[0,1,1]
	v_pk_fma_f32 v[122:123], v[62:63], v[168:169], v[122:123] op_sel_hi:[0,1,1]
	v_pk_mul_f32 v[122:123], v[122:123], v[124:125]
	v_lshlrev_b32_e32 v124, 16, v167
	v_and_b32_e32 v125, 0xffff0000, v167
	v_pk_fma_f32 v[124:125], v[134:135], v[124:125], v[126:127] op_sel_hi:[0,1,1]
	v_pk_mul_f32 v[124:125], v[172:173], v[124:125]
	v_cvt_pk_bf16_f32 v122, v122, v123
	v_cvt_pk_bf16_f32 v123, v124, v125
	v_and_b32_e32 v167, 0xffff0000, v129
	flat_store_dwordx2 v[60:61], v[122:123]
	v_lshlrev_b32_e32 v126, 16, v129
	v_and_b32_e32 v166, 16, v129
	v_mov_b32_e32 v127, v167
	ds_read_b64 v[122:123], v164 offset:32
	v_lshlrev_b32_e32 v85, 16, v131
	v_lshlrev_b32_e32 v131, 16, v128
	v_and_b32_e32 v124, 0xffff0000, v128
	v_pk_mov_b32 v[128:129], v[166:167], v[126:127] op_sel:[1,0]
	s_waitcnt lgkmcnt(0)
	v_lshlrev_b32_e32 v168, 16, v122
	v_mov_b32_e32 v125, v129
	v_pk_fma_f32 v[166:167], v[66:67], v[124:125], v[68:69] op_sel_hi:[0,1,0]
	v_mov_b32_e32 v129, v85
	v_pk_fma_f32 v[166:167], v[64:65], v[126:127], v[166:167] op_sel_hi:[0,1,1]
	v_pk_fma_f32 v[128:129], v[62:63], v[128:129], v[166:167] op_sel_hi:[0,1,1]
	v_pk_fma_f32 v[166:167], v[66:67], v[130:131], v[68:69] op_sel_hi:[0,1,0]
	v_pk_mov_b32 v[130:131], v[130:131], v[124:125] op_sel:[1,0]
	v_and_b32_e32 v169, 0xffff0000, v122
	v_pk_fma_f32 v[130:131], v[64:65], v[130:131], v[166:167] op_sel_hi:[0,1,1]
	v_mov_b32_e32 v125, v126
	v_lshlrev_b32_e32 v122, 16, v123
	v_and_b32_e32 v123, 0xffff0000, v123
	v_pk_fma_f32 v[56:57], v[134:135], v[168:169], v[56:57] op_sel_hi:[0,1,1]
	v_pk_fma_f32 v[124:125], v[62:63], v[124:125], v[130:131] op_sel_hi:[0,1,1]
	v_pk_fma_f32 v[58:59], v[134:135], v[122:123], v[58:59] op_sel_hi:[0,1,1]
	v_pk_mul_f32 v[56:57], v[124:125], v[56:57]
	v_pk_mul_f32 v[58:59], v[128:129], v[58:59]
	v_cvt_pk_bf16_f32 v56, v56, v57
	v_cvt_pk_bf16_f32 v57, v58, v59
	flat_store_dwordx2 v[60:61], v[56:57] offset:32
	ds_read_b64 v[56:57], v164 offset:64
	v_and_b32_e32 v123, 0xffff0000, v121
	v_lshlrev_b32_e32 v85, 16, v133
	v_lshlrev_b32_e32 v133, 16, v120
	v_and_b32_e32 v58, 0xffff0000, v120
	v_lshlrev_b32_e32 v120, 16, v121
	v_and_b32_e32 v122, 16, v121
	v_mov_b32_e32 v121, v123
	v_pk_mov_b32 v[122:123], v[122:123], v[120:121] op_sel:[1,0]
	s_waitcnt lgkmcnt(0)
	v_lshlrev_b32_e32 v126, 16, v56
	v_mov_b32_e32 v59, v123
	v_pk_fma_f32 v[124:125], v[66:67], v[58:59], v[68:69] op_sel_hi:[0,1,0]
	v_mov_b32_e32 v123, v85
	v_pk_fma_f32 v[124:125], v[64:65], v[120:121], v[124:125] op_sel_hi:[0,1,1]
	v_and_b32_e32 v127, 0xffff0000, v56
	v_pk_fma_f32 v[122:123], v[62:63], v[122:123], v[124:125] op_sel_hi:[0,1,1]
	v_pk_fma_f32 v[124:125], v[66:67], v[132:133], v[68:69] op_sel_hi:[0,1,0]
	v_pk_fma_f32 v[52:53], v[134:135], v[126:127], v[52:53] op_sel_hi:[0,1,1]
	v_pk_mov_b32 v[126:127], v[132:133], v[58:59] op_sel:[1,0]
	v_mov_b32_e32 v59, v120
	v_pk_fma_f32 v[124:125], v[64:65], v[126:127], v[124:125] op_sel_hi:[0,1,1]
	v_lshlrev_b32_e32 v56, 16, v57
	v_and_b32_e32 v57, 0xffff0000, v57
	v_pk_fma_f32 v[58:59], v[62:63], v[58:59], v[124:125] op_sel_hi:[0,1,1]
	v_pk_fma_f32 v[54:55], v[134:135], v[56:57], v[54:55] op_sel_hi:[0,1,1]
	v_pk_mul_f32 v[52:53], v[58:59], v[52:53]
	v_pk_mul_f32 v[54:55], v[122:123], v[54:55]
	v_cvt_pk_bf16_f32 v52, v52, v53
	v_cvt_pk_bf16_f32 v53, v54, v55
	flat_store_dwordx2 v[60:61], v[52:53] offset:64
	ds_read_b64 v[52:53], v164 offset:96
	v_and_b32_e32 v59, 0xffff0000, v117
	v_lshlrev_b32_e32 v56, 16, v117
	v_and_b32_e32 v58, 16, v117
	v_mov_b32_e32 v57, v59
	v_pk_mov_b32 v[58:59], v[58:59], v[56:57] op_sel:[1,0]
	v_and_b32_e32 v54, 0xffff0000, v116
	v_mov_b32_e32 v55, v59
	v_lshlrev_b32_e32 v85, 16, v135
	v_lshlrev_b32_e32 v137, 16, v116
	v_pk_fma_f32 v[116:117], v[66:67], v[54:55], v[68:69] op_sel_hi:[0,1,0]
	v_mov_b32_e32 v59, v85
	v_pk_fma_f32 v[116:117], v[64:65], v[56:57], v[116:117] op_sel_hi:[0,1,1]
	s_waitcnt lgkmcnt(0)
	v_lshlrev_b32_e32 v120, 16, v52
	v_and_b32_e32 v121, 0xffff0000, v52
	v_pk_fma_f32 v[58:59], v[62:63], v[58:59], v[116:117] op_sel_hi:[0,1,1]
	v_pk_fma_f32 v[116:117], v[66:67], v[136:137], v[68:69] op_sel_hi:[0,1,0]
	v_pk_fma_f32 v[48:49], v[134:135], v[120:121], v[48:49] op_sel_hi:[0,1,1]
	v_pk_mov_b32 v[120:121], v[136:137], v[54:55] op_sel:[1,0]
	v_mov_b32_e32 v55, v56
	v_pk_fma_f32 v[116:117], v[64:65], v[120:121], v[116:117] op_sel_hi:[0,1,1]
	v_lshlrev_b32_e32 v52, 16, v53
	v_and_b32_e32 v53, 0xffff0000, v53
	v_pk_fma_f32 v[54:55], v[62:63], v[54:55], v[116:117] op_sel_hi:[0,1,1]
	v_pk_fma_f32 v[50:51], v[134:135], v[52:53], v[50:51] op_sel_hi:[0,1,1]
	v_cndmask_b32_e64 v89, v112, v108, s[12:13]
	v_pk_mul_f32 v[48:49], v[54:55], v[48:49]
	v_pk_mul_f32 v[50:51], v[58:59], v[50:51]
	ds_bpermute_b32 v89, v163, v89
	v_cvt_pk_bf16_f32 v48, v48, v49
	v_cvt_pk_bf16_f32 v49, v50, v51
	flat_store_dwordx2 v[60:61], v[48:49] offset:96
	ds_read_b64 v[48:49], v164 offset:128
	v_and_b32_e32 v55, 0xffff0000, v113
	v_lshlrev_b32_e32 v52, 16, v113
	v_and_b32_e32 v54, 16, v113
	v_mov_b32_e32 v53, v55
	v_pk_mov_b32 v[54:55], v[54:55], v[52:53] op_sel:[1,0]
	s_waitcnt lgkmcnt(0)
	v_lshlrev_b32_e32 v56, 16, v89
	v_and_b32_e32 v50, 0xffff0000, v112
	v_mov_b32_e32 v51, v55
	v_mov_b32_e32 v55, v56
	v_pk_fma_f32 v[56:57], v[66:67], v[50:51], v[68:69] op_sel_hi:[0,1,0]
	v_lshlrev_b32_e32 v119, 16, v112
	v_pk_fma_f32 v[56:57], v[64:65], v[52:53], v[56:57] op_sel_hi:[0,1,1]
	v_lshlrev_b32_e32 v58, 16, v48
	v_and_b32_e32 v59, 0xffff0000, v48
	v_pk_fma_f32 v[54:55], v[62:63], v[54:55], v[56:57] op_sel_hi:[0,1,1]
	v_pk_fma_f32 v[56:57], v[66:67], v[118:119], v[68:69] op_sel_hi:[0,1,0]
	v_pk_fma_f32 v[44:45], v[134:135], v[58:59], v[44:45] op_sel_hi:[0,1,1]
	v_pk_mov_b32 v[58:59], v[118:119], v[50:51] op_sel:[1,0]
	v_mov_b32_e32 v51, v52
	v_pk_fma_f32 v[56:57], v[64:65], v[58:59], v[56:57] op_sel_hi:[0,1,1]
	v_lshlrev_b32_e32 v48, 16, v49
	v_and_b32_e32 v49, 0xffff0000, v49
	v_pk_fma_f32 v[50:51], v[62:63], v[50:51], v[56:57] op_sel_hi:[0,1,1]
	v_pk_fma_f32 v[46:47], v[134:135], v[48:49], v[46:47] op_sel_hi:[0,1,1]
	v_cndmask_b32_e64 v91, v108, v104, s[12:13]
	v_pk_mul_f32 v[44:45], v[50:51], v[44:45]
	v_pk_mul_f32 v[46:47], v[54:55], v[46:47]
	ds_bpermute_b32 v91, v163, v91
	v_cvt_pk_bf16_f32 v44, v44, v45
	v_cvt_pk_bf16_f32 v45, v46, v47
	v_cndmask_b32_e64 v98, v101, v105, s[10:11]
	v_cndmask_b32_e64 v115, v79, v83, s[10:11]
	flat_store_dwordx2 v[60:61], v[44:45] offset:128
	ds_bpermute_b32 v88, v162, v98
	ds_bpermute_b32 v115, v162, v115
	ds_read_b64 v[44:45], v164 offset:160
	v_and_b32_e32 v51, 0xffff0000, v109
	v_lshlrev_b32_e32 v48, 16, v109
	v_and_b32_e32 v50, 16, v109
	v_mov_b32_e32 v49, v51
	v_pk_mov_b32 v[50:51], v[50:51], v[48:49] op_sel:[1,0]
	s_waitcnt lgkmcnt(0)
	v_lshlrev_b32_e32 v52, 16, v91
	v_and_b32_e32 v46, 0xffff0000, v108
	v_mov_b32_e32 v47, v51
	v_cndmask_b32_e64 v106, v93, v97, s[10:11]
	v_mov_b32_e32 v51, v52
	v_pk_fma_f32 v[52:53], v[66:67], v[46:47], v[68:69] op_sel_hi:[0,1,0]
	ds_bpermute_b32 v94, v162, v106
	v_and_b32_e32 v106, 0xffff0000, v88
	v_and_b32_e32 v88, 0xffff0000, v115
	v_lshlrev_b32_e32 v115, 16, v108
	v_pk_fma_f32 v[52:53], v[64:65], v[48:49], v[52:53] op_sel_hi:[0,1,1]
	v_lshlrev_b32_e32 v54, 16, v44
	v_and_b32_e32 v55, 0xffff0000, v44
	v_pk_fma_f32 v[50:51], v[62:63], v[50:51], v[52:53] op_sel_hi:[0,1,1]
	v_pk_fma_f32 v[52:53], v[66:67], v[114:115], v[68:69] op_sel_hi:[0,1,0]
	v_pk_fma_f32 v[40:41], v[134:135], v[54:55], v[40:41] op_sel_hi:[0,1,1]
	v_pk_mov_b32 v[54:55], v[114:115], v[46:47] op_sel:[1,0]
	v_mov_b32_e32 v47, v48
	v_pk_fma_f32 v[52:53], v[64:65], v[54:55], v[52:53] op_sel_hi:[0,1,1]
	v_lshlrev_b32_e32 v44, 16, v45
	v_and_b32_e32 v45, 0xffff0000, v45
	v_pk_fma_f32 v[46:47], v[62:63], v[46:47], v[52:53] op_sel_hi:[0,1,1]
	v_pk_fma_f32 v[42:43], v[134:135], v[44:45], v[42:43] op_sel_hi:[0,1,1]
	v_cndmask_b32_e64 v95, v104, v100, s[12:13]
	v_pk_mul_f32 v[40:41], v[46:47], v[40:41]
	v_pk_mul_f32 v[42:43], v[50:51], v[42:43]
	ds_bpermute_b32 v95, v163, v95
	v_cvt_pk_bf16_f32 v40, v40, v41
	v_cvt_pk_bf16_f32 v41, v42, v43
	v_cndmask_b32_e64 v102, v97, v101, s[10:11]
	flat_store_dwordx2 v[60:61], v[40:41] offset:160
	ds_bpermute_b32 v90, v162, v102
	ds_read_b64 v[40:41], v164 offset:192
	v_and_b32_e32 v47, 0xffff0000, v105
	v_lshlrev_b32_e32 v44, 16, v105
	v_and_b32_e32 v46, 16, v105
	v_mov_b32_e32 v45, v47
	v_pk_mov_b32 v[46:47], v[46:47], v[44:45] op_sel:[1,0]
	s_waitcnt lgkmcnt(0)
	v_lshlrev_b32_e32 v48, 16, v95
	v_and_b32_e32 v42, 0xffff0000, v104
	v_mov_b32_e32 v43, v47
	v_mov_b32_e32 v47, v48
	v_pk_fma_f32 v[48:49], v[66:67], v[42:43], v[68:69] op_sel_hi:[0,1,0]
	v_and_b32_e32 v102, 0xffff0000, v90
	v_and_b32_e32 v90, 0xffff0000, v111
	v_lshlrev_b32_e32 v111, 16, v104
	v_pk_fma_f32 v[48:49], v[64:65], v[44:45], v[48:49] op_sel_hi:[0,1,1]
	v_lshlrev_b32_e32 v50, 16, v40
	v_and_b32_e32 v51, 0xffff0000, v40
	v_pk_fma_f32 v[46:47], v[62:63], v[46:47], v[48:49] op_sel_hi:[0,1,1]
	v_pk_fma_f32 v[48:49], v[66:67], v[110:111], v[68:69] op_sel_hi:[0,1,0]
	v_pk_fma_f32 v[36:37], v[134:135], v[50:51], v[36:37] op_sel_hi:[0,1,1]
	v_pk_mov_b32 v[50:51], v[110:111], v[42:43] op_sel:[1,0]
	v_mov_b32_e32 v43, v44
	v_pk_fma_f32 v[48:49], v[64:65], v[50:51], v[48:49] op_sel_hi:[0,1,1]
	v_lshlrev_b32_e32 v40, 16, v41
	v_and_b32_e32 v41, 0xffff0000, v41
	v_pk_fma_f32 v[42:43], v[62:63], v[42:43], v[48:49] op_sel_hi:[0,1,1]
	v_pk_fma_f32 v[38:39], v[134:135], v[40:41], v[38:39] op_sel_hi:[0,1,1]
	v_cndmask_b32_e64 v99, v100, v96, s[12:13]
	v_pk_mul_f32 v[36:37], v[42:43], v[36:37]
	v_pk_mul_f32 v[38:39], v[46:47], v[38:39]
	ds_bpermute_b32 v99, v163, v99
	v_cvt_pk_bf16_f32 v36, v36, v37
	v_cvt_pk_bf16_f32 v37, v38, v39
	flat_store_dwordx2 v[60:61], v[36:37] offset:192
	ds_read_b64 v[36:37], v164 offset:224
	v_and_b32_e32 v43, 0xffff0000, v101
	v_lshlrev_b32_e32 v40, 16, v101
	v_and_b32_e32 v42, 16, v101
	v_mov_b32_e32 v41, v43
	v_pk_mov_b32 v[42:43], v[42:43], v[40:41] op_sel:[1,0]
	s_waitcnt lgkmcnt(0)
	v_lshlrev_b32_e32 v44, 16, v99
	v_and_b32_e32 v38, 0xffff0000, v100
	v_mov_b32_e32 v39, v43
	v_mov_b32_e32 v43, v44
	v_pk_fma_f32 v[44:45], v[66:67], v[38:39], v[68:69] op_sel_hi:[0,1,0]
	v_and_b32_e32 v98, 0xffff0000, v94
	v_and_b32_e32 v94, 0xffff0000, v107
	v_lshlrev_b32_e32 v107, 16, v100
	v_pk_fma_f32 v[44:45], v[64:65], v[40:41], v[44:45] op_sel_hi:[0,1,1]
	v_lshlrev_b32_e32 v46, 16, v36
	v_and_b32_e32 v47, 0xffff0000, v36
	v_pk_fma_f32 v[42:43], v[62:63], v[42:43], v[44:45] op_sel_hi:[0,1,1]
	v_pk_fma_f32 v[44:45], v[66:67], v[106:107], v[68:69] op_sel_hi:[0,1,0]
	v_pk_fma_f32 v[32:33], v[134:135], v[46:47], v[32:33] op_sel_hi:[0,1,1]
	v_pk_mov_b32 v[46:47], v[106:107], v[38:39] op_sel:[1,0]
	v_mov_b32_e32 v39, v40
	v_pk_fma_f32 v[44:45], v[64:65], v[46:47], v[44:45] op_sel_hi:[0,1,1]
	v_lshlrev_b32_e32 v36, 16, v37
	v_and_b32_e32 v37, 0xffff0000, v37
	v_pk_fma_f32 v[38:39], v[62:63], v[38:39], v[44:45] op_sel_hi:[0,1,1]
	v_pk_fma_f32 v[34:35], v[134:135], v[36:37], v[34:35] op_sel_hi:[0,1,1]
	v_cndmask_b32_e64 v103, v96, v92, s[12:13]
	v_pk_mul_f32 v[32:33], v[38:39], v[32:33]
	v_pk_mul_f32 v[34:35], v[42:43], v[34:35]
	ds_bpermute_b32 v103, v163, v103
	v_cvt_pk_bf16_f32 v32, v32, v33
	v_cvt_pk_bf16_f32 v33, v34, v35
	flat_store_dwordx2 v[60:61], v[32:33] offset:224
	ds_read_b64 v[32:33], v164 offset:256
	v_and_b32_e32 v39, 0xffff0000, v97
	v_lshlrev_b32_e32 v36, 16, v97
	v_and_b32_e32 v38, 16, v97
	v_mov_b32_e32 v37, v39
	v_pk_mov_b32 v[38:39], v[38:39], v[36:37] op_sel:[1,0]
	s_waitcnt lgkmcnt(0)
	v_lshlrev_b32_e32 v40, 16, v103
	v_and_b32_e32 v34, 0xffff0000, v96
	v_mov_b32_e32 v35, v39
	v_mov_b32_e32 v39, v40
	v_pk_fma_f32 v[40:41], v[66:67], v[34:35], v[68:69] op_sel_hi:[0,1,0]
	v_lshlrev_b32_e32 v103, 16, v96
	v_pk_fma_f32 v[40:41], v[64:65], v[36:37], v[40:41] op_sel_hi:[0,1,1]
	v_lshlrev_b32_e32 v42, 16, v32
	v_and_b32_e32 v43, 0xffff0000, v32
	v_pk_fma_f32 v[38:39], v[62:63], v[38:39], v[40:41] op_sel_hi:[0,1,1]
	v_pk_fma_f32 v[40:41], v[66:67], v[102:103], v[68:69] op_sel_hi:[0,1,0]
	v_pk_fma_f32 v[28:29], v[134:135], v[42:43], v[28:29] op_sel_hi:[0,1,1]
	v_pk_mov_b32 v[42:43], v[102:103], v[34:35] op_sel:[1,0]
	v_mov_b32_e32 v35, v36
	v_pk_fma_f32 v[40:41], v[64:65], v[42:43], v[40:41] op_sel_hi:[0,1,1]
	v_lshlrev_b32_e32 v32, 16, v33
	v_and_b32_e32 v33, 0xffff0000, v33
	v_pk_fma_f32 v[34:35], v[62:63], v[34:35], v[40:41] op_sel_hi:[0,1,1]
	v_pk_fma_f32 v[30:31], v[134:135], v[32:33], v[30:31] op_sel_hi:[0,1,1]
	v_pk_mul_f32 v[28:29], v[34:35], v[28:29]
	v_pk_mul_f32 v[30:31], v[38:39], v[30:31]
	v_cvt_pk_bf16_f32 v28, v28, v29
	v_cvt_pk_bf16_f32 v29, v30, v31
	flat_store_dwordx2 v[60:61], v[28:29] offset:256
	ds_read_b64 v[28:29], v164 offset:288
	v_and_b32_e32 v35, 0xffff0000, v93
	v_lshlrev_b32_e32 v32, 16, v93
	v_and_b32_e32 v34, 16, v93
	v_mov_b32_e32 v33, v35
	v_pk_mov_b32 v[34:35], v[34:35], v[32:33] op_sel:[1,0]
	v_lshlrev_b32_e32 v36, 16, v165
	v_and_b32_e32 v30, 0xffff0000, v92
	v_mov_b32_e32 v31, v35
	v_mov_b32_e32 v35, v36
	v_pk_fma_f32 v[36:37], v[66:67], v[30:31], v[68:69] op_sel_hi:[0,1,0]
	v_lshlrev_b32_e32 v99, 16, v92
	v_pk_fma_f32 v[36:37], v[64:65], v[32:33], v[36:37] op_sel_hi:[0,1,1]
	s_waitcnt lgkmcnt(0)
	v_lshlrev_b32_e32 v38, 16, v28
	v_and_b32_e32 v39, 0xffff0000, v28
	v_pk_fma_f32 v[34:35], v[62:63], v[34:35], v[36:37] op_sel_hi:[0,1,1]
	v_pk_fma_f32 v[36:37], v[66:67], v[98:99], v[68:69] op_sel_hi:[0,1,0]
	v_pk_fma_f32 v[24:25], v[134:135], v[38:39], v[24:25] op_sel_hi:[0,1,1]
	v_pk_mov_b32 v[38:39], v[98:99], v[30:31] op_sel:[1,0]
	v_mov_b32_e32 v31, v32
	v_pk_fma_f32 v[36:37], v[64:65], v[38:39], v[36:37] op_sel_hi:[0,1,1]
	v_lshlrev_b32_e32 v28, 16, v29
	v_and_b32_e32 v29, 0xffff0000, v29
	v_pk_fma_f32 v[30:31], v[62:63], v[30:31], v[36:37] op_sel_hi:[0,1,1]
	v_pk_fma_f32 v[26:27], v[134:135], v[28:29], v[26:27] op_sel_hi:[0,1,1]
	v_pk_mul_f32 v[24:25], v[30:31], v[24:25]
	v_pk_mul_f32 v[26:27], v[34:35], v[26:27]
	v_cvt_pk_bf16_f32 v24, v24, v25
	v_cvt_pk_bf16_f32 v25, v26, v27
	flat_store_dwordx2 v[60:61], v[24:25] offset:288
	ds_read_b64 v[24:25], v164 offset:320
	v_and_b32_e32 v31, 0xffff0000, v87
	v_lshlrev_b32_e32 v28, 16, v87
	v_and_b32_e32 v30, 16, v87
	v_mov_b32_e32 v29, v31
	v_pk_mov_b32 v[30:31], v[30:31], v[28:29] op_sel:[1,0]
	v_lshlrev_b32_e32 v32, 16, v81
	v_and_b32_e32 v26, 0xffff0000, v86
	v_mov_b32_e32 v27, v31
	v_mov_b32_e32 v31, v32
	v_pk_fma_f32 v[32:33], v[66:67], v[26:27], v[68:69] op_sel_hi:[0,1,0]
	v_lshlrev_b32_e32 v95, 16, v86
	v_pk_fma_f32 v[32:33], v[64:65], v[28:29], v[32:33] op_sel_hi:[0,1,1]
	s_waitcnt lgkmcnt(0)
	v_lshlrev_b32_e32 v34, 16, v24
	v_and_b32_e32 v35, 0xffff0000, v24
	v_pk_fma_f32 v[30:31], v[62:63], v[30:31], v[32:33] op_sel_hi:[0,1,1]
	v_pk_fma_f32 v[32:33], v[66:67], v[94:95], v[68:69] op_sel_hi:[0,1,0]
	v_pk_fma_f32 v[20:21], v[134:135], v[34:35], v[20:21] op_sel_hi:[0,1,1]
	v_pk_mov_b32 v[34:35], v[94:95], v[26:27] op_sel:[1,0]
	v_mov_b32_e32 v27, v28
	v_pk_fma_f32 v[32:33], v[64:65], v[34:35], v[32:33] op_sel_hi:[0,1,1]
	v_lshlrev_b32_e32 v24, 16, v25
	v_and_b32_e32 v25, 0xffff0000, v25
	v_pk_fma_f32 v[26:27], v[62:63], v[26:27], v[32:33] op_sel_hi:[0,1,1]
	v_pk_fma_f32 v[22:23], v[134:135], v[24:25], v[22:23] op_sel_hi:[0,1,1]
	v_pk_mul_f32 v[20:21], v[26:27], v[20:21]
	v_pk_mul_f32 v[22:23], v[30:31], v[22:23]
	v_cvt_pk_bf16_f32 v20, v20, v21
	v_cvt_pk_bf16_f32 v21, v22, v23
	flat_store_dwordx2 v[60:61], v[20:21] offset:320
	ds_read_b64 v[20:21], v164 offset:352
	v_and_b32_e32 v27, 0xffff0000, v83
	v_lshlrev_b32_e32 v24, 16, v83
	v_and_b32_e32 v26, 16, v83
	v_mov_b32_e32 v25, v27
	v_pk_mov_b32 v[26:27], v[26:27], v[24:25] op_sel:[1,0]
	v_lshlrev_b32_e32 v28, 16, v77
	v_and_b32_e32 v22, 0xffff0000, v82
	v_mov_b32_e32 v23, v27
	v_mov_b32_e32 v27, v28
	v_pk_fma_f32 v[28:29], v[66:67], v[22:23], v[68:69] op_sel_hi:[0,1,0]
	v_lshlrev_b32_e32 v91, 16, v82
	v_pk_fma_f32 v[28:29], v[64:65], v[24:25], v[28:29] op_sel_hi:[0,1,1]
	s_waitcnt lgkmcnt(0)
	v_lshlrev_b32_e32 v30, 16, v20
	v_and_b32_e32 v31, 0xffff0000, v20
	v_pk_fma_f32 v[26:27], v[62:63], v[26:27], v[28:29] op_sel_hi:[0,1,1]
	v_pk_fma_f32 v[28:29], v[66:67], v[90:91], v[68:69] op_sel_hi:[0,1,0]
	v_pk_fma_f32 v[16:17], v[134:135], v[30:31], v[16:17] op_sel_hi:[0,1,1]
	v_pk_mov_b32 v[30:31], v[90:91], v[22:23] op_sel:[1,0]
	v_mov_b32_e32 v23, v24
	v_pk_fma_f32 v[28:29], v[64:65], v[30:31], v[28:29] op_sel_hi:[0,1,1]
	v_lshlrev_b32_e32 v20, 16, v21
	v_and_b32_e32 v21, 0xffff0000, v21
	v_pk_fma_f32 v[22:23], v[62:63], v[22:23], v[28:29] op_sel_hi:[0,1,1]
	v_pk_fma_f32 v[18:19], v[134:135], v[20:21], v[18:19] op_sel_hi:[0,1,1]
	v_pk_mul_f32 v[16:17], v[22:23], v[16:17]
	v_pk_mul_f32 v[18:19], v[26:27], v[18:19]
	v_cvt_pk_bf16_f32 v16, v16, v17
	v_cvt_pk_bf16_f32 v17, v18, v19
	flat_store_dwordx2 v[60:61], v[16:17] offset:352
	ds_read_b64 v[16:17], v164 offset:384
	v_and_b32_e32 v23, 0xffff0000, v79
	v_lshlrev_b32_e32 v20, 16, v79
	v_and_b32_e32 v22, 16, v79
	v_mov_b32_e32 v21, v23
	v_pk_mov_b32 v[22:23], v[22:23], v[20:21] op_sel:[1,0]
	v_lshlrev_b32_e32 v24, 16, v69
	v_and_b32_e32 v18, 0xffff0000, v78
	v_mov_b32_e32 v19, v23
	v_mov_b32_e32 v23, v24
	v_pk_fma_f32 v[24:25], v[66:67], v[18:19], v[68:69] op_sel_hi:[0,1,0]
	v_lshlrev_b32_e32 v89, 16, v78
	v_pk_fma_f32 v[24:25], v[64:65], v[20:21], v[24:25] op_sel_hi:[0,1,1]
	s_waitcnt lgkmcnt(0)
	v_lshlrev_b32_e32 v26, 16, v16
	v_and_b32_e32 v27, 0xffff0000, v16
	v_pk_fma_f32 v[22:23], v[62:63], v[22:23], v[24:25] op_sel_hi:[0,1,1]
	v_pk_fma_f32 v[24:25], v[66:67], v[88:89], v[68:69] op_sel_hi:[0,1,0]
	v_pk_fma_f32 v[12:13], v[134:135], v[26:27], v[12:13] op_sel_hi:[0,1,1]
	v_pk_mov_b32 v[26:27], v[88:89], v[18:19] op_sel:[1,0]
	v_mov_b32_e32 v19, v20
	v_pk_fma_f32 v[24:25], v[64:65], v[26:27], v[24:25] op_sel_hi:[0,1,1]
	v_lshlrev_b32_e32 v16, 16, v17
	v_and_b32_e32 v17, 0xffff0000, v17
	v_pk_fma_f32 v[18:19], v[62:63], v[18:19], v[24:25] op_sel_hi:[0,1,1]
	v_pk_fma_f32 v[14:15], v[134:135], v[16:17], v[14:15] op_sel_hi:[0,1,1]
	v_pk_mul_f32 v[12:13], v[18:19], v[12:13]
	v_pk_mul_f32 v[14:15], v[22:23], v[14:15]
	v_cvt_pk_bf16_f32 v12, v12, v13
	v_cvt_pk_bf16_f32 v13, v14, v15
	flat_store_dwordx2 v[60:61], v[12:13] offset:384
	ds_read_b64 v[12:13], v164 offset:416
	v_and_b32_e32 v19, 0xffff0000, v75
	v_lshlrev_b32_e32 v16, 16, v75
	v_and_b32_e32 v18, 16, v75
	v_mov_b32_e32 v17, v19
	v_pk_mov_b32 v[18:19], v[18:19], v[16:17] op_sel:[1,0]
	v_lshlrev_b32_e32 v20, 16, v67
	v_and_b32_e32 v14, 0xffff0000, v74
	v_mov_b32_e32 v15, v19
	v_mov_b32_e32 v19, v20
	v_pk_fma_f32 v[20:21], v[66:67], v[14:15], v[68:69] op_sel_hi:[0,1,0]
	v_lshlrev_b32_e32 v85, 16, v74
	v_pk_fma_f32 v[20:21], v[64:65], v[16:17], v[20:21] op_sel_hi:[0,1,1]
	s_waitcnt lgkmcnt(0)
	v_lshlrev_b32_e32 v22, 16, v12
	v_and_b32_e32 v23, 0xffff0000, v12
	v_pk_fma_f32 v[18:19], v[62:63], v[18:19], v[20:21] op_sel_hi:[0,1,1]
	v_pk_fma_f32 v[20:21], v[66:67], v[84:85], v[68:69] op_sel_hi:[0,1,0]
	v_pk_fma_f32 v[8:9], v[134:135], v[22:23], v[8:9] op_sel_hi:[0,1,1]
	v_pk_mov_b32 v[22:23], v[84:85], v[14:15] op_sel:[1,0]
	v_mov_b32_e32 v15, v16
	v_pk_fma_f32 v[20:21], v[64:65], v[22:23], v[20:21] op_sel_hi:[0,1,1]
	v_lshlrev_b32_e32 v12, 16, v13
	v_and_b32_e32 v13, 0xffff0000, v13
	v_pk_fma_f32 v[14:15], v[62:63], v[14:15], v[20:21] op_sel_hi:[0,1,1]
	v_pk_fma_f32 v[10:11], v[134:135], v[12:13], v[10:11] op_sel_hi:[0,1,1]
	v_pk_mul_f32 v[8:9], v[14:15], v[8:9]
	v_pk_mul_f32 v[10:11], v[18:19], v[10:11]
	v_cvt_pk_bf16_f32 v8, v8, v9
	v_cvt_pk_bf16_f32 v9, v10, v11
	flat_store_dwordx2 v[60:61], v[8:9] offset:416
	ds_read_b64 v[8:9], v164 offset:448
	v_and_b32_e32 v15, 0xffff0000, v73
	v_lshlrev_b32_e32 v12, 16, v73
	v_and_b32_e32 v14, 16, v73
	v_mov_b32_e32 v13, v15
	v_pk_mov_b32 v[14:15], v[14:15], v[12:13] op_sel:[1,0]
	v_lshlrev_b32_e32 v16, 16, v65
	v_and_b32_e32 v10, 0xffff0000, v72
	v_mov_b32_e32 v11, v15
	v_mov_b32_e32 v15, v16
	v_pk_fma_f32 v[16:17], v[66:67], v[10:11], v[68:69] op_sel_hi:[0,1,0]
	v_lshlrev_b32_e32 v81, 16, v72
	v_pk_fma_f32 v[16:17], v[64:65], v[12:13], v[16:17] op_sel_hi:[0,1,1]
	s_waitcnt lgkmcnt(0)
	v_lshlrev_b32_e32 v18, 16, v8
	v_and_b32_e32 v19, 0xffff0000, v8
	v_pk_fma_f32 v[14:15], v[62:63], v[14:15], v[16:17] op_sel_hi:[0,1,1]
	v_pk_fma_f32 v[16:17], v[66:67], v[80:81], v[68:69] op_sel_hi:[0,1,0]
	v_pk_fma_f32 v[4:5], v[134:135], v[18:19], v[4:5] op_sel_hi:[0,1,1]
	v_pk_mov_b32 v[18:19], v[80:81], v[10:11] op_sel:[1,0]
	v_mov_b32_e32 v11, v12
	v_pk_fma_f32 v[16:17], v[64:65], v[18:19], v[16:17] op_sel_hi:[0,1,1]
	v_lshlrev_b32_e32 v8, 16, v9
	v_and_b32_e32 v9, 0xffff0000, v9
	v_pk_fma_f32 v[10:11], v[62:63], v[10:11], v[16:17] op_sel_hi:[0,1,1]
	v_pk_fma_f32 v[6:7], v[134:135], v[8:9], v[6:7] op_sel_hi:[0,1,1]
	v_pk_mul_f32 v[4:5], v[10:11], v[4:5]
	v_pk_mul_f32 v[6:7], v[14:15], v[6:7]
	v_cvt_pk_bf16_f32 v4, v4, v5
	v_cvt_pk_bf16_f32 v5, v6, v7
	flat_store_dwordx2 v[60:61], v[4:5] offset:448
	ds_read_b64 v[4:5], v164 offset:480
	v_and_b32_e32 v11, 0xffff0000, v71
	v_lshlrev_b32_e32 v8, 16, v71
	v_and_b32_e32 v10, 16, v71
	v_mov_b32_e32 v9, v11
	v_pk_mov_b32 v[10:11], v[10:11], v[8:9] op_sel:[1,0]
	v_lshlrev_b32_e32 v12, 16, v63
	v_and_b32_e32 v6, 0xffff0000, v70
	v_mov_b32_e32 v7, v11
	v_mov_b32_e32 v11, v12
	v_pk_fma_f32 v[12:13], v[66:67], v[6:7], v[68:69] op_sel_hi:[0,1,0]
	v_and_b32_e32 v76, 0xffff0000, v76
	v_lshlrev_b32_e32 v77, 16, v70
	v_pk_fma_f32 v[12:13], v[64:65], v[8:9], v[12:13] op_sel_hi:[0,1,1]
	s_waitcnt lgkmcnt(0)
	v_lshlrev_b32_e32 v14, 16, v4
	v_and_b32_e32 v15, 0xffff0000, v4
	v_pk_fma_f32 v[10:11], v[62:63], v[10:11], v[12:13] op_sel_hi:[0,1,1]
	v_pk_fma_f32 v[12:13], v[66:67], v[76:77], v[68:69] op_sel_hi:[0,1,0]
	v_pk_fma_f32 v[0:1], v[134:135], v[14:15], v[0:1] op_sel_hi:[0,1,1]
	v_pk_mov_b32 v[14:15], v[76:77], v[6:7] op_sel:[1,0]
	v_mov_b32_e32 v7, v8
	v_pk_fma_f32 v[12:13], v[64:65], v[14:15], v[12:13] op_sel_hi:[0,1,1]
	v_lshlrev_b32_e32 v4, 16, v5
	v_and_b32_e32 v5, 0xffff0000, v5
	v_pk_fma_f32 v[6:7], v[62:63], v[6:7], v[12:13] op_sel_hi:[0,1,1]
	v_pk_fma_f32 v[2:3], v[134:135], v[4:5], v[2:3] op_sel_hi:[0,1,1]
	v_pk_mul_f32 v[0:1], v[6:7], v[0:1]
	v_pk_mul_f32 v[2:3], v[10:11], v[2:3]
	v_cvt_pk_bf16_f32 v0, v0, v1
	v_cvt_pk_bf16_f32 v1, v2, v3
	flat_store_dwordx2 v[60:61], v[0:1] offset:480
	s_cbranch_scc1 .LBB0_449
